# RG-LRU gate sigmoids use v_rcp_f32 instead of the IEEE division expansion; in-projection epilogue stores without the non-temporal hint
# speedup vs baseline: 1.0027x; 1.0027x over previous
.LBB0_256:
	s_or_b64 exec, exec, s[0:1]
	s_load_dwordx4 s[4:7], s[72:73], 0xa8
	v_lshlrev_b32_e32 v83, 2, v2
	v_or_b32_e32 v50, 1, v48
	s_movk_i32 s15, 0x900
	s_movk_i32 s25, 0x90
	s_waitcnt lgkmcnt(0)
	v_lshl_add_u64 v[0:1], s[4:5], 0, v[124:125]
	global_load_dword v38, v124, s[4:5]
	global_load_dword v39, v124, s[6:7]
	global_load_dword v42, v124, s[4:5] offset:2048
	v_add_co_u32_e32 v0, vcc, 0x1000, v0
	v_or_b32_e32 v52, 2, v48
	s_nop 0
	v_addc_co_u32_e32 v1, vcc, 0, v1, vcc
	global_load_dword v43, v[0:1], off
	global_load_dword v44, v[0:1], off offset:2048
	v_lshlrev_b32_e32 v0, 1, v2
	v_sub_u32_e32 v0, v83, v0
	v_mad_u64_u32 v[22:23], s[20:21], v49, s15, v[0:1]
	v_mad_u64_u32 v[0:1], s[20:21], v50, s25, v[0:1]
	v_or_b32_e32 v54, 3, v48
	v_or_b32_e32 v56, 4, v48
	v_or_b32_e32 v58, 5, v48
	v_or_b32_e32 v60, 6, v48
	v_lshl_or_b32 v105, v49, 12, v83
	s_load_dwordx2 s[0:1], s[72:73], 0xc0
	s_load_dwordx4 s[4:7], s[72:73], 0xd0
	v_lshl_or_b32 v104, v50, 8, v83
	v_lshl_or_b32 v53, v52, 8, v83
	v_lshl_or_b32 v55, v54, 8, v83
	v_lshl_or_b32 v57, v56, 8, v83
	v_lshl_or_b32 v59, v58, 8, v83
	v_lshl_or_b32 v61, v60, 8, v83
	v_or_b32_e32 v64, 8, v48
	v_lshl_or_b32 v65, v64, 8, v83
	v_or_b32_e32 v66, 9, v48
	v_lshl_or_b32 v67, v66, 8, v83
	v_or_b32_e32 v68, 10, v48
	v_lshl_or_b32 v69, v68, 8, v83
	v_or_b32_e32 v70, 11, v48
	v_lshl_or_b32 v71, v70, 8, v83
	s_lshl_b32 s78, s14, 14
	s_mov_b64 s[14:15], 0x4c36000
	v_or_b32_e32 v62, 7, v48
	v_lshl_or_b32 v63, v62, 8, v83
	v_or_b32_e32 v72, 12, v48
	v_lshl_or_b32 v73, v72, 8, v83
	v_or_b32_e32 v74, 13, v48
	v_lshl_or_b32 v75, v74, 8, v83
	v_or_b32_e32 v76, 14, v48
	v_lshl_or_b32 v77, v76, 8, v83
	v_or_b32_e32 v78, 15, v48
	v_lshl_or_b32 v79, v78, 8, v83
	v_and_b32_e32 v89, 31, v51
	v_lshrrev_b32_e32 v91, 5, v2
	v_ashrrev_i32_e32 v92, 2, v51
	s_waitcnt vmcnt(3)
	v_fma_f32 v1, v5, v38, v39
	v_fma_f32 v5, v3, v38, v39
	v_fma_f32 v23, v7, v38, v39
	v_fma_f32 v24, v6, v38, v39
	v_fma_f32 v25, v11, v38, v39
	v_fma_f32 v26, v10, v38, v39
	v_fma_f32 v27, v19, v38, v39
	s_waitcnt vmcnt(2)
	v_fmac_f32_e32 v1, v3, v42
	v_fma_f32 v28, v18, v38, v39
	v_fmac_f32_e32 v5, v7, v42
	v_fmac_f32_e32 v23, v6, v42
	v_fmac_f32_e32 v24, v11, v42
	v_fmac_f32_e32 v25, v10, v42
	v_fmac_f32_e32 v26, v19, v42
	v_fmac_f32_e32 v27, v18, v42
	s_waitcnt vmcnt(1)
	v_fmac_f32_e32 v1, v7, v43
	v_fmac_f32_e32 v28, v14, v42
	v_fmac_f32_e32 v5, v6, v43
	v_fmac_f32_e32 v23, v11, v43
	v_fmac_f32_e32 v24, v10, v43
	v_fmac_f32_e32 v25, v19, v43
	v_fmac_f32_e32 v26, v18, v43
	v_fmac_f32_e32 v27, v14, v43
	s_waitcnt vmcnt(0)
	v_fmac_f32_e32 v1, v6, v44
	v_fmac_f32_e32 v28, v12, v43
	v_fmac_f32_e32 v5, v11, v44
	v_fmac_f32_e32 v23, v10, v44
	v_fmac_f32_e32 v24, v19, v44
	v_fmac_f32_e32 v25, v18, v44
	v_fmac_f32_e32 v26, v14, v44
	v_fmac_f32_e32 v27, v12, v44
	v_bfe_u32 v3, v1, 16, 1
	v_fmac_f32_e32 v28, v17, v44
	ds_write_b32 v105, v1 offset:9216
	v_bfe_u32 v6, v5, 16, 1
	v_bfe_u32 v7, v23, 16, 1
	v_bfe_u32 v10, v24, 16, 1
	v_bfe_u32 v11, v25, 16, 1
	v_bfe_u32 v18, v26, 16, 1
	v_bfe_u32 v19, v27, 16, 1
	v_add3_u32 v1, v1, v3, s33
	ds_write_b32 v104, v5 offset:9216
	ds_write_b32 v53, v23 offset:9216
	ds_write_b32 v55, v24 offset:9216
	ds_write_b32 v57, v25 offset:9216
	ds_write_b32 v59, v26 offset:9216
	ds_write_b32 v61, v27 offset:9216
	v_add3_u32 v3, v5, v6, s33
	v_add3_u32 v5, v23, v7, s33
	v_add3_u32 v6, v24, v10, s33
	v_add3_u32 v7, v25, v11, s33
	v_add3_u32 v10, v26, v18, s33
	v_add3_u32 v11, v27, v19, s33
	ds_write_b16_d16_hi v22, v1
	ds_write_b16_d16_hi v0, v3
	ds_write_b16_d16_hi v0, v5 offset:144
	ds_write_b16_d16_hi v0, v6 offset:288
	ds_write_b16_d16_hi v0, v7 offset:432
	ds_write_b16_d16_hi v0, v10 offset:576
	ds_write_b16_d16_hi v0, v11 offset:720
	v_bfe_u32 v1, v28, 16, 1
	v_add3_u32 v1, v28, v1, s33
	ds_write_b16_d16_hi v0, v1 offset:864
	v_fma_f32 v1, v14, v38, v39
	v_fmac_f32_e32 v1, v12, v42
	v_fmac_f32_e32 v1, v17, v43
	v_fmac_f32_e32 v1, v16, v44
	v_bfe_u32 v3, v1, 16, 1
	ds_write_b32 v65, v1 offset:9216
	v_add3_u32 v1, v1, v3, s33
	ds_write_b16_d16_hi v0, v1 offset:1008
	v_fma_f32 v1, v12, v38, v39
	v_fmac_f32_e32 v1, v17, v42
	v_fmac_f32_e32 v1, v16, v43
	v_fmac_f32_e32 v1, v20, v44
	v_bfe_u32 v3, v1, 16, 1
	ds_write_b32 v67, v1 offset:9216
	v_add3_u32 v1, v1, v3, s33
	ds_write_b16_d16_hi v0, v1 offset:1152
	v_fma_f32 v1, v17, v38, v39
	v_fmac_f32_e32 v1, v16, v42
	v_fmac_f32_e32 v1, v20, v43
	v_fmac_f32_e32 v1, v4, v44
	v_bfe_u32 v3, v1, 16, 1
	ds_write_b32 v69, v1 offset:9216
	v_add3_u32 v1, v1, v3, s33
	ds_write_b16_d16_hi v0, v1 offset:1296
	v_fma_f32 v1, v16, v38, v39
	v_fmac_f32_e32 v1, v20, v42
	v_fmac_f32_e32 v1, v4, v43
	v_fmac_f32_e32 v1, v9, v44
	v_bfe_u32 v3, v1, 16, 1
	ds_write_b32 v71, v1 offset:9216
	v_add3_u32 v1, v1, v3, s33
	v_lshlrev_b32_e32 v3, 3, v51
	v_lshlrev_b32_e32 v5, 4, v51
	v_and_b32_e32 v30, 0xffffffc0, v3
	v_and_b32_e32 v6, 0x70, v5
	v_mov_b32_e32 v7, v125
	v_ashrrev_i32_e32 v31, 31, v30
	v_lshl_add_u64 v[10:11], s[12:13], 0, v[6:7]
	v_lshlrev_b64 v[34:35], 1, v[30:31]
	v_add_u32_e32 v22, 0x800, v30
	v_add_u32_e32 v26, 0x1000, v30
	v_add_u32_e32 v30, 0x1800, v30
	v_lshl_add_u64 v[10:11], v[10:11], 0, s[78:79]
	v_ashrrev_i32_e32 v23, 31, v22
	v_ashrrev_i32_e32 v27, 31, v26
	v_ashrrev_i32_e32 v31, 31, v30
	v_lshl_add_u64 v[32:33], v[10:11], 0, s[14:15]
	v_lshlrev_b64 v[36:37], 1, v[22:23]
	v_lshlrev_b64 v[40:41], 1, v[26:27]
	v_lshlrev_b64 v[30:31], 1, v[30:31]
	v_lshl_add_u64 v[16:17], v[32:33], 0, v[34:35]
	v_lshl_add_u64 v[22:23], v[32:33], 0, v[36:37]
	v_lshl_add_u64 v[26:27], v[32:33], 0, v[40:41]
	v_lshl_add_u64 v[32:33], v[32:33], 0, v[30:31]
	ds_write_b32 v63, v28 offset:9216
	global_load_dwordx4 v[16:19], v[16:17], off
	ds_write_b16_d16_hi v0, v1 offset:1440
	global_load_dwordx4 v[22:25], v[22:23], off
	v_fma_f32 v1, v20, v38, v39
	global_load_dwordx4 v[26:29], v[26:27], off
	v_fmac_f32_e32 v1, v4, v42
	global_load_dwordx4 v[94:97], v[32:33], off
	v_fmac_f32_e32 v1, v9, v43
	v_fmac_f32_e32 v1, v8, v44
	v_bfe_u32 v3, v1, 16, 1
	ds_write_b32 v73, v1 offset:9216
	v_add3_u32 v1, v1, v3, s33
	ds_write_b16_d16_hi v0, v1 offset:1584
	v_fma_f32 v1, v4, v38, v39
	v_fmac_f32_e32 v1, v9, v42
	v_fmac_f32_e32 v1, v8, v43
	v_fmac_f32_e32 v1, v15, v44
	v_bfe_u32 v3, v1, 16, 1
	ds_write_b32 v75, v1 offset:9216
	v_add3_u32 v1, v1, v3, s33
	ds_write_b16_d16_hi v0, v1 offset:1728
	v_fma_f32 v1, v9, v38, v39
	v_fmac_f32_e32 v1, v8, v42
	v_fmac_f32_e32 v1, v15, v43
	v_fmac_f32_e32 v39, v8, v38
	v_fmac_f32_e32 v1, v13, v44
	v_fmac_f32_e32 v39, v15, v42
	v_bfe_u32 v3, v1, 16, 1
	v_fmac_f32_e32 v39, v13, v43
	ds_write_b32 v77, v1 offset:9216
	v_add3_u32 v1, v1, v3, s33
	v_fmac_f32_e32 v39, v21, v44
	ds_write_b16_d16_hi v0, v1 offset:1872
	v_bfe_u32 v1, v39, 16, 1
	v_add3_u32 v1, v39, v1, s33
	s_mov_b64 s[14:15], 0x4c56000
	ds_write_b16_d16_hi v0, v1 offset:2016
	v_lshl_add_u64 v[0:1], v[10:11], 0, s[14:15]
	ds_write_b32 v79, v39 offset:9216
	v_lshl_add_u64 v[4:5], v[0:1], 0, v[34:35]
	v_lshl_add_u64 v[8:9], v[0:1], 0, v[36:37]
	global_load_dwordx4 v[32:35], v[4:5], off
	global_load_dwordx4 v[36:39], v[8:9], off
	v_lshl_add_u64 v[4:5], v[0:1], 0, v[40:41]
	v_lshl_add_u64 v[0:1], v[0:1], 0, v[30:31]
	global_load_dwordx4 v[40:43], v[4:5], off
	global_load_dwordx4 v[44:47], v[0:1], off
	v_lshlrev_b32_e32 v0, 5, v49
	v_and_b32_e32 v90, 32, v0
	v_or_b32_e32 v5, v90, v89
	v_or_b32_e32 v0, s11, v5
	v_lshlrev_b32_e32 v0, 2, v0
	s_waitcnt lgkmcnt(0)
	global_load_dword v88, v0, s[0:1]
	global_load_dword v86, v0, s[4:5]
	global_load_dword v93, v0, s[6:7]
	global_load_dword v84, v0, s[4:5] offset:2048
	global_load_dword v87, v0, s[6:7] offset:2048
	global_load_dword v85, v0, s[0:1] offset:2048
	s_movk_i32 s0, 0xffe0
	v_bfi_b32 v0, s0, v92, v51
	v_lshlrev_b32_e32 v4, 4, v91
	v_mad_u64_u32 v[80:81], s[0:1], v0, s25, v[4:5]
	v_lshrrev_b32_e32 v0, 3, v51
	v_mul_lo_u32 v0, v0, s25
	v_add_u32_e32 v100, v6, v0
	v_add_u32_e32 v0, 0x100, v51
	v_lshrrev_b32_e32 v0, 3, v0
	v_mul_lo_u32 v0, v0, s25
	v_add_u32_e32 v101, v6, v0
	v_add_u32_e32 v0, 0x200, v51
	v_lshrrev_b32_e32 v0, 3, v0
	v_mul_lo_u32 v0, v0, s25
	v_add_u32_e32 v102, v6, v0
	v_add_u32_e32 v0, 0x300, v51
	v_lshrrev_b32_e32 v0, 3, v0
	v_mul_lo_u32 v0, v0, s25
	v_add_u32_e32 v103, v6, v0
	v_mad_u32_u24 v99, v5, s25, v4
	s_mov_b32 s0, 0xbfb8aa3b
	s_waitcnt vmcnt(13)
	ds_write_b128 v100, v[16:19] offset:25600
	s_waitcnt vmcnt(12)
	ds_write_b128 v101, v[22:25] offset:25600
	s_waitcnt vmcnt(11)
	ds_write_b128 v102, v[26:29] offset:25600
	s_waitcnt vmcnt(10)
	ds_write_b128 v103, v[94:97] offset:25600
	s_waitcnt lgkmcnt(0)
	s_barrier
	ds_read_b128 v[0:3], v80
	ds_read_b128 v[4:7], v99 offset:25600
	s_waitcnt lgkmcnt(0)
	v_mfma_f32_32x32x16_bf16 v[16:31], v[0:3], v[4:7], 0
	ds_read_b128 v[4:7], v99 offset:34816
	ds_read_b128 v[94:97], v80 offset:32
	ds_read_b128 v[106:109], v99 offset:25632
	s_waitcnt vmcnt(3)
	v_mul_f32_e32 v81, 0xbfb8aa3b, v93
	s_waitcnt lgkmcnt(2)
	v_mfma_f32_32x32x16_bf16 v[0:15], v[0:3], v[4:7], 0
	v_fma_f32 v98, v93, s0, -v81
	v_fmac_f32_e32 v98, 0xb2a5705f, v93
	s_mov_b32 s0, 0x42ce8ed0
	v_cmp_nlt_f32_e32 vcc, s0, v93
	s_mov_b32 s0, 0xc2b17218
	s_waitcnt lgkmcnt(0)
	v_mfma_f32_32x32x16_bf16 v[16:31], v[94:97], v[106:109], v[16:31]
	ds_read_b128 v[106:109], v99 offset:34848
	s_waitcnt lgkmcnt(0)
	v_mfma_f32_32x32x16_bf16 v[0:15], v[94:97], v[106:109], v[0:15]
	ds_read_b128 v[94:97], v80 offset:64
	ds_read_b128 v[106:109], v99 offset:25664
	s_waitcnt lgkmcnt(0)
	v_mfma_f32_32x32x16_bf16 v[16:31], v[94:97], v[106:109], v[16:31]
	ds_read_b128 v[106:109], v99 offset:34880
	s_waitcnt lgkmcnt(0)
	v_mfma_f32_32x32x16_bf16 v[0:15], v[94:97], v[106:109], v[0:15]
	ds_read_b128 v[94:97], v80 offset:96
	ds_read_b128 v[106:109], v99 offset:25696
	ds_read_b128 v[110:113], v99 offset:34912
	s_waitcnt lgkmcnt(1)
	v_mfma_f32_32x32x16_bf16 v[16:31], v[94:97], v[106:109], v[16:31]
	v_rndne_f32_e32 v106, v81
	v_sub_f32_e32 v81, v81, v106
	v_add_f32_e32 v81, v81, v98
	v_exp_f32_e32 v81, v81
	v_cvt_i32_f32_e32 v98, v106
	s_nop 6
	v_add_f32_e32 v16, v88, v16
	v_ldexp_f32 v81, v81, v98
	v_cndmask_b32_e32 v81, 0, v81, vcc
	v_cmp_ngt_f32_e32 vcc, s0, v93
	s_waitcnt lgkmcnt(0)
	v_mfma_f32_32x32x16_bf16 v[0:15], v[94:97], v[110:113], v[0:15]
	s_mov_b32 s0, 0x3f2aaaab
	v_cndmask_b32_e32 v81, v170, v81, vcc
	v_add_f32_e32 v93, 1.0, v81
	v_add_f32_e32 v94, -1.0, v93
	v_sub_f32_e32 v95, v94, v93
	v_add_f32_e32 v95, 1.0, v95
	v_sub_f32_e32 v94, v81, v94
	v_add_f32_e32 v96, v94, v95
	v_frexp_mant_f32_e32 v97, v93
	v_cvt_f64_f32_e32 v[94:95], v93
	v_frexp_exp_i32_f64_e32 v94, v[94:95]
	v_cmp_gt_f32_e32 vcc, s0, v97
	s_mov_b32 s0, 0x3f317218
	v_mul_f32_e32 v16, 0xbfb8aa3b, v16
	v_subbrev_co_u32_e32 v98, vcc, 0, v94, vcc
	v_sub_u32_e32 v94, 0, v98
	v_ldexp_f32 v93, v93, v94
	v_ldexp_f32 v94, v96, v94
	v_add_f32_e32 v96, -1.0, v93
	v_add_f32_e32 v95, 1.0, v96
	v_sub_f32_e32 v95, v93, v95
	v_add_f32_e32 v97, v94, v95
	v_add_f32_e32 v95, 1.0, v93
	v_add_f32_e32 v106, -1.0, v95
	v_sub_f32_e32 v93, v93, v106
	v_add_f32_e32 v93, v94, v93
	v_add_f32_e32 v110, v95, v93
	v_rcp_f32_e32 v111, v110
	v_sub_f32_e32 v94, v95, v110
	v_add_f32_e32 v95, v96, v97
	v_add_f32_e32 v93, v93, v94
	v_mul_f32_e32 v113, v95, v111
	v_sub_f32_e32 v94, v96, v95
	v_mul_f32_e32 v96, v110, v113
	v_fma_f32 v106, v113, v110, -v96
	v_fmac_f32_e32 v106, v113, v93
	v_add_f32_e32 v112, v97, v94
	v_add_f32_e32 v94, v96, v106
	v_sub_f32_e32 v97, v95, v94
	v_pk_add_f32 v[108:109], v[94:95], v[96:97] neg_lo:[0,1] neg_hi:[0,1]
	v_mov_b32_e32 v107, v94
	v_pk_add_f32 v[94:95], v[108:109], v[106:107] neg_lo:[0,1] neg_hi:[0,1]
	v_exp_f32_e32 v16, v16
	v_add_f32_e32 v95, v112, v95
	v_add_f32_e32 v94, v94, v95
	v_add_f32_e32 v95, v97, v94
	v_mul_f32_e32 v112, v111, v95
	v_mul_f32_e32 v96, v110, v112
	v_fma_f32 v106, v112, v110, -v96
	v_fmac_f32_e32 v106, v112, v93
	v_sub_f32_e32 v93, v97, v95
	v_add_f32_e32 v93, v94, v93
	v_add_f32_e32 v94, v96, v106
	v_sub_f32_e32 v97, v95, v94
	v_pk_add_f32 v[108:109], v[94:95], v[96:97] neg_lo:[0,1] neg_hi:[0,1]
	v_mov_b32_e32 v107, v94
	v_pk_add_f32 v[94:95], v[108:109], v[106:107] neg_lo:[0,1] neg_hi:[0,1]
	v_cmp_neq_f32_e32 vcc, s94, v81
	v_add_f32_e32 v93, v93, v95
	v_add_f32_e32 v93, v94, v93
	v_add_f32_e32 v95, v113, v112
	v_add_f32_e32 v93, v97, v93
	v_sub_f32_e32 v94, v95, v113
	v_mul_f32_e32 v93, v111, v93
	v_sub_f32_e32 v94, v112, v94
	v_add_f32_e32 v93, v94, v93
	v_add_f32_e32 v96, v95, v93
	v_mul_f32_e32 v106, v96, v96
	v_fmamk_f32 v94, v106, 0x3e9b6dac, v157
	v_fmaak_f32 v129, v106, v94, 0x3f2aaada
	v_cvt_f32_i32_e32 v94, v98
	v_sub_f32_e32 v95, v96, v95
	v_sub_f32_e32 v93, v93, v95
	v_mul_f32_e32 v95, v96, v106
	v_pk_mul_f32 v[106:107], v[94:95], v[128:129]
	v_ldexp_f32 v97, v96, 1
	v_fma_f32 v96, v94, s0, -v106
	v_fmac_f32_e32 v96, 0xb102e308, v94
	v_pk_add_f32 v[94:95], v[106:107], v[96:97]
	v_ldexp_f32 v93, v93, 1
	v_sub_f32_e32 v97, v95, v97
	v_sub_f32_e32 v97, v107, v97
	v_add_f32_e32 v109, v93, v97
	v_mov_b32_e32 v108, v106
	v_pk_add_f32 v[106:107], v[94:95], v[106:107] neg_lo:[0,1] neg_hi:[0,1]
	v_pk_add_f32 v[110:111], v[94:95], v[108:109]
	v_mov_b32_e32 v97, v94
	v_mov_b32_e32 v107, v111
	v_pk_add_f32 v[112:113], v[96:97], v[106:107] neg_lo:[0,1] neg_hi:[0,1]
	v_pk_add_f32 v[96:97], v[96:97], v[106:107]
	v_mov_b32_e32 v108, v109
	v_pk_add_f32 v[106:107], v[96:97], v[94:95] op_sel:[1,0] op_sel_hi:[0,1] neg_lo:[0,1] neg_hi:[0,1]
	v_pk_add_f32 v[114:115], v[110:111], v[106:107] op_sel_hi:[1,0] neg_lo:[0,1] neg_hi:[0,1]
	v_mov_b32_e32 v110, v111
	v_mov_b32_e32 v111, v97
	v_pk_mov_b32 v[106:107], v[94:95], v[106:107] op_sel:[1,0]
	v_mov_b32_e32 v109, v94
	v_pk_add_f32 v[106:107], v[110:111], v[106:107] neg_lo:[0,1] neg_hi:[0,1]
	v_mov_b32_e32 v114, v112
	v_pk_add_f32 v[94:95], v[108:109], v[106:107] neg_lo:[0,1] neg_hi:[0,1]
	v_mov_b32_e32 v113, v97
	v_pk_add_f32 v[106:107], v[114:115], v[94:95]
	s_nop 0
	v_pk_add_f32 v[108:109], v[106:107], v[106:107] op_sel:[0,1] op_sel_hi:[1,0]
	s_nop 0
	v_pk_add_f32 v[96:97], v[96:97], v[108:109] op_sel:[1,0] op_sel_hi:[0,1]
	v_mov_b32_e32 v107, v96
	v_pk_add_f32 v[110:111], v[106:107], v[112:113] neg_lo:[0,1] neg_hi:[0,1]
	v_mov_b32_e32 v95, v108
	v_sub_f32_e32 v93, v106, v110
	v_pk_add_f32 v[94:95], v[94:95], v[110:111] neg_lo:[0,1] neg_hi:[0,1]
	v_sub_f32_e32 v93, v112, v93
	v_add_f32_e32 v93, v94, v93
	v_add_f32_e32 v94, 1.0, v16
	v_add_f32_e32 v93, v93, v95
	v_add_f32_e32 v93, v96, v93
	s_mov_b32 s0, 0x33800000
	v_cndmask_b32_e32 v16, v170, v93, vcc
	v_cmp_lt_f32_e64 vcc, |v81|, s0
	s_nop 1
	v_cndmask_b32_e32 v16, v16, v81, vcc
	v_rcp_f32_e64 v81, -v94
	s_nop 0
	v_mul_f32_e32 v81, 0x41000000, v81
	v_mul_f32_e32 v93, v81, v16
	v_fmamk_f32 v81, v93, 0x3ab60b61, v158
	v_fmaak_f32 v81, v93, v81, 0x3d2aaaab
	v_fmaak_f32 v81, v93, v81, 0x3e2aaaab
	v_fma_f32 v81, v93, v81, 0.5
	v_fma_f32 v81, v93, v81, 1.0
	v_mul_f32_e32 v81, v93, v81
	v_cmp_gt_f32_e32 vcc, s95, v93
	s_and_saveexec_b64 s[0:1], vcc
	s_cbranch_execz .LBB0_258
	v_mul_f32_e32 v81, 0x3fb8aa3b, v93
	v_rndne_f32_e32 v81, v81
	v_fmamk_f32 v94, v81, 0xbf317218, v93
	v_fmac_f32_e32 v94, 0x3102e308, v81
	v_fmamk_f32 v95, v94, 0x395133b1, v159
	v_cmp_eq_f32_e32 vcc, s96, v81
	v_cvt_i32_f32_e32 v81, v81
	v_fmaak_f32 v95, v94, v95, 0x3c0887f9
	v_fmaak_f32 v95, v94, v95, 0x3d2aaa81
	v_fmaak_f32 v95, v94, v95, 0x3e2aaaab
	v_fma_f32 v95, v94, v95, 0.5
	v_ldexp_f32 v81, 1.0, v81
	v_mul_f32_e32 v95, v94, v95
	v_cndmask_b32_e32 v81, v81, v171, vcc
	v_fmac_f32_e32 v94, v94, v95
	v_add_f32_e32 v95, -1.0, v81
	v_fmac_f32_e32 v95, v81, v94
	v_add_f32_e32 v81, v95, v95
	v_cndmask_b32_e32 v81, v95, v81, vcc
	v_cmp_ngt_f32_e32 vcc, s97, v93
	s_nop 1
	v_cndmask_b32_e32 v81, -1.0, v81, vcc
.LBB0_258:
	s_or_b64 exec, exec, s[0:1]
	v_add_f32_e32 v0, v86, v0
	v_mul_f32_e32 v0, 0xbfb8aa3b, v0
	v_exp_f32_e32 v0, v0
	v_and_b32_e32 v92, 0xffffffe0, v92
	v_lshlrev_b32_e32 v91, 8, v91
	v_add_f32_e32 v17, v88, v17
	v_add_f32_e32 v0, 1.0, v0
	v_mul_f32_e32 v17, 0xbfb8aa3b, v17
	v_exp_f32_e32 v17, v17
	v_rcp_f32_e32 v93, v0
	s_nop 0
	v_add_f32_e32 v0, 2.0, v81
	v_mul_f32_e64 v0, v0, -v81
	v_add_f32_e32 v94, 1.0, v81
	v_cmp_gt_f32_e32 vcc, s28, v0
	v_mul_f32_e32 v81, 0x4f800000, v0
	v_add_f32_e32 v17, 1.0, v17
	v_cndmask_b32_e32 v0, v0, v81, vcc
	v_sqrt_f32_e32 v81, v0
	s_nop 0
	v_add_u32_e32 v95, -1, v81
	v_fma_f32 v96, -v95, v81, v0
	v_cmp_ge_f32_e64 s[0:1], 0, v96
	v_add_u32_e32 v96, 1, v81
	s_nop 0
	v_cndmask_b32_e64 v95, v81, v95, s[0:1]
	v_fma_f32 v81, -v96, v81, v0
	v_cmp_lt_f32_e64 s[0:1], 0, v81
	s_nop 1
	v_cndmask_b32_e64 v81, v95, v96, s[0:1]
	v_mul_f32_e32 v95, 0x37800000, v81
	v_cndmask_b32_e32 v81, v81, v95, vcc
	v_cmp_class_f32_e32 vcc, v0, v160
	s_nop 1
	v_cndmask_b32_e32 v95, v81, v0, vcc
	v_lshl_or_b32 v0, v92, 6, v91
	v_or3_b32 v0, v0, v89, v90
	v_lshlrev_b32_e32 v81, 2, v0
	ds_read_b32 v89, v81 offset:9216
	s_waitcnt lgkmcnt(0)
	v_mul_f32_e32 v89, v93, v89
	v_mul_f32_e32 v89, v89, v95
	ds_write2st64_b32 v81, v94, v89 offset0:172 offset1:236
	s_nop 0
	v_rcp_f32_e32 v17, v17
	s_nop 0
	v_mul_f32_e32 v17, 0xc1000000, v17
	v_mul_f32_e32 v89, v17, v16
	v_fmamk_f32 v17, v89, 0x3ab60b61, v158
	v_fmaak_f32 v17, v89, v17, 0x3d2aaaab
	v_fmaak_f32 v17, v89, v17, 0x3e2aaaab
	v_fma_f32 v17, v89, v17, 0.5
	v_fma_f32 v17, v89, v17, 1.0
	v_mul_f32_e32 v17, v89, v17
	v_cmp_gt_f32_e32 vcc, s95, v89
	s_and_saveexec_b64 s[0:1], vcc
	s_cbranch_execz .LBB0_260
	v_mul_f32_e32 v17, 0x3fb8aa3b, v89
	v_rndne_f32_e32 v17, v17
	v_fmamk_f32 v90, v17, 0xbf317218, v89
	v_fmac_f32_e32 v90, 0x3102e308, v17
	v_fmamk_f32 v91, v90, 0x395133b1, v159
	v_cmp_eq_f32_e32 vcc, s96, v17
	v_cvt_i32_f32_e32 v17, v17
	v_fmaak_f32 v91, v90, v91, 0x3c0887f9
	v_fmaak_f32 v91, v90, v91, 0x3d2aaa81
	v_fmaak_f32 v91, v90, v91, 0x3e2aaaab
	v_fma_f32 v91, v90, v91, 0.5
	v_ldexp_f32 v17, 1.0, v17
	v_mul_f32_e32 v91, v90, v91
	v_cndmask_b32_e32 v17, v17, v171, vcc
	v_fmac_f32_e32 v90, v90, v91
	v_add_f32_e32 v91, -1.0, v17
	v_fmac_f32_e32 v91, v17, v90
	v_add_f32_e32 v17, v91, v91
	v_cndmask_b32_e32 v17, v91, v17, vcc
	v_cmp_ngt_f32_e32 vcc, s97, v89
	s_nop 1
	v_cndmask_b32_e32 v17, -1.0, v17, vcc
.LBB0_260:
	s_or_b64 exec, exec, s[0:1]
	v_add_f32_e32 v1, v86, v1
	v_mul_f32_e32 v1, 0xbfb8aa3b, v1
	v_exp_f32_e32 v1, v1
	s_nop 0
	v_add_f32_e32 v1, 1.0, v1
	s_nop 0
	v_add_f32_e32 v90, 2.0, v17
	v_rcp_f32_e32 v1, v1
	s_nop 0
	v_add_f32_e32 v89, 1.0, v17
	v_mul_f32_e64 v17, v90, -v17
	v_cmp_gt_f32_e32 vcc, s28, v17
	v_mul_f32_e32 v90, 0x4f800000, v17
	s_nop 0
	v_cndmask_b32_e32 v17, v17, v90, vcc
	v_sqrt_f32_e32 v90, v17
	s_nop 0
	v_add_u32_e32 v91, -1, v90
	v_fma_f32 v92, -v91, v90, v17
	v_cmp_ge_f32_e64 s[0:1], 0, v92
	v_add_u32_e32 v92, 1, v90
	s_nop 0
	v_cndmask_b32_e64 v91, v90, v91, s[0:1]
	v_fma_f32 v90, -v92, v90, v17
	v_cmp_lt_f32_e64 s[0:1], 0, v90
	s_nop 1
	v_cndmask_b32_e64 v90, v91, v92, s[0:1]
	v_mul_f32_e32 v91, 0x37800000, v90
	v_cndmask_b32_e32 v90, v90, v91, vcc
	v_cmp_class_f32_e32 vcc, v17, v160
	s_nop 1
	v_cndmask_b32_e32 v17, v90, v17, vcc
	ds_read_b32 v90, v81 offset:9472
	s_waitcnt lgkmcnt(0)
	v_mul_f32_e32 v1, v1, v90
	v_mul_f32_e32 v1, v1, v17
	ds_write2st64_b32 v81, v89, v1 offset0:173 offset1:237
	v_add_f32_e32 v1, v88, v18
	v_mul_f32_e32 v1, 0xbfb8aa3b, v1
	v_exp_f32_e32 v1, v1
	s_nop 0
	v_add_f32_e32 v1, 1.0, v1
	s_nop 0
	v_rcp_f32_e32 v1, v1
	s_nop 0
	v_mul_f32_e32 v1, 0xc1000000, v1
	v_mul_f32_e32 v17, v1, v16
	v_fmamk_f32 v1, v17, 0x3ab60b61, v158
	v_fmaak_f32 v1, v17, v1, 0x3d2aaaab
	v_fmaak_f32 v1, v17, v1, 0x3e2aaaab
	v_fma_f32 v1, v17, v1, 0.5
	v_fma_f32 v1, v17, v1, 1.0
	v_mul_f32_e32 v1, v17, v1
	v_cmp_gt_f32_e32 vcc, s95, v17
	s_and_saveexec_b64 s[0:1], vcc
	s_cbranch_execz .LBB0_262
	v_mul_f32_e32 v1, 0x3fb8aa3b, v17
	v_rndne_f32_e32 v1, v1
	v_fmamk_f32 v18, v1, 0xbf317218, v17
	v_fmac_f32_e32 v18, 0x3102e308, v1
	v_fmamk_f32 v89, v18, 0x395133b1, v159
	v_cmp_eq_f32_e32 vcc, s96, v1
	v_cvt_i32_f32_e32 v1, v1
	v_fmaak_f32 v89, v18, v89, 0x3c0887f9
	v_fmaak_f32 v89, v18, v89, 0x3d2aaa81
	v_fmaak_f32 v89, v18, v89, 0x3e2aaaab
	v_fma_f32 v89, v18, v89, 0.5
	v_ldexp_f32 v1, 1.0, v1
	v_mul_f32_e32 v89, v18, v89
	v_cndmask_b32_e32 v1, v1, v171, vcc
	v_fmac_f32_e32 v18, v18, v89
	v_add_f32_e32 v89, -1.0, v1
	v_fmac_f32_e32 v89, v1, v18
	v_add_f32_e32 v1, v89, v89
	v_cndmask_b32_e32 v1, v89, v1, vcc
	v_cmp_ngt_f32_e32 vcc, s97, v17
	s_nop 1
	v_cndmask_b32_e32 v1, -1.0, v1, vcc
.LBB0_262:
	s_or_b64 exec, exec, s[0:1]
	v_add_f32_e32 v2, v86, v2
	v_mul_f32_e32 v2, 0xbfb8aa3b, v2
	v_exp_f32_e32 v2, v2
	s_nop 0
	v_add_f32_e32 v2, 1.0, v2
	s_nop 0
	v_add_f32_e32 v18, 2.0, v1
	v_rcp_f32_e32 v2, v2
	s_nop 0
	v_add_f32_e32 v17, 1.0, v1
	v_mul_f32_e64 v1, v18, -v1
	v_cmp_gt_f32_e32 vcc, s28, v1
	v_mul_f32_e32 v18, 0x4f800000, v1
	s_nop 0
	v_cndmask_b32_e32 v1, v1, v18, vcc
	v_sqrt_f32_e32 v18, v1
	s_nop 0
	v_add_u32_e32 v89, -1, v18
	v_fma_f32 v90, -v89, v18, v1
	v_cmp_ge_f32_e64 s[0:1], 0, v90
	v_add_u32_e32 v90, 1, v18
	s_nop 0
	v_cndmask_b32_e64 v89, v18, v89, s[0:1]
	v_fma_f32 v18, -v90, v18, v1
	v_cmp_lt_f32_e64 s[0:1], 0, v18
	s_nop 1
	v_cndmask_b32_e64 v18, v89, v90, s[0:1]
	v_mul_f32_e32 v89, 0x37800000, v18
	v_cndmask_b32_e32 v18, v18, v89, vcc
	v_cmp_class_f32_e32 vcc, v1, v160
	s_nop 1
	v_cndmask_b32_e32 v1, v18, v1, vcc
	ds_read_b32 v18, v81 offset:9728
	s_waitcnt lgkmcnt(0)
	v_mul_f32_e32 v2, v2, v18
	v_mul_f32_e32 v1, v2, v1
	ds_write2st64_b32 v81, v17, v1 offset0:174 offset1:238
	v_add_f32_e32 v1, v88, v19
	v_mul_f32_e32 v1, 0xbfb8aa3b, v1
	v_exp_f32_e32 v1, v1
	s_nop 0
	v_add_f32_e32 v1, 1.0, v1
	s_nop 0
	v_rcp_f32_e32 v1, v1
	s_nop 0
	v_mul_f32_e32 v1, 0xc1000000, v1
	v_mul_f32_e32 v2, v1, v16
	v_fmamk_f32 v1, v2, 0x3ab60b61, v158
	v_fmaak_f32 v1, v2, v1, 0x3d2aaaab
	v_fmaak_f32 v1, v2, v1, 0x3e2aaaab
	v_fma_f32 v1, v2, v1, 0.5
	v_fma_f32 v1, v2, v1, 1.0
	v_mul_f32_e32 v1, v2, v1
	v_cmp_gt_f32_e32 vcc, s95, v2
	s_and_saveexec_b64 s[0:1], vcc
	s_cbranch_execz .LBB0_264
	v_mul_f32_e32 v1, 0x3fb8aa3b, v2
	v_rndne_f32_e32 v1, v1
	v_fmamk_f32 v17, v1, 0xbf317218, v2
	v_fmac_f32_e32 v17, 0x3102e308, v1
	v_fmamk_f32 v18, v17, 0x395133b1, v159
	v_cmp_eq_f32_e32 vcc, s96, v1
	v_cvt_i32_f32_e32 v1, v1
	v_fmaak_f32 v18, v17, v18, 0x3c0887f9
	v_fmaak_f32 v18, v17, v18, 0x3d2aaa81
	v_fmaak_f32 v18, v17, v18, 0x3e2aaaab
	v_fma_f32 v18, v17, v18, 0.5
	v_ldexp_f32 v1, 1.0, v1
	v_mul_f32_e32 v18, v17, v18
	v_cndmask_b32_e32 v1, v1, v171, vcc
	v_fmac_f32_e32 v17, v17, v18
	v_add_f32_e32 v18, -1.0, v1
	v_fmac_f32_e32 v18, v1, v17
	v_add_f32_e32 v1, v18, v18
	v_cndmask_b32_e32 v1, v18, v1, vcc
	v_cmp_ngt_f32_e32 vcc, s97, v2
	s_nop 1
	v_cndmask_b32_e32 v1, -1.0, v1, vcc
.LBB0_264:
	s_or_b64 exec, exec, s[0:1]
	v_add_f32_e32 v2, v86, v3
	v_mul_f32_e32 v2, 0xbfb8aa3b, v2
	v_exp_f32_e32 v2, v2
	s_nop 0
	v_add_f32_e32 v2, 1.0, v2
	s_nop 0
	v_add_f32_e32 v17, 2.0, v1
	v_rcp_f32_e32 v2, v2
	s_nop 0
	v_add_f32_e32 v3, 1.0, v1
	v_mul_f32_e64 v1, v17, -v1
	v_cmp_gt_f32_e32 vcc, s28, v1
	v_mul_f32_e32 v17, 0x4f800000, v1
	s_nop 0
	v_cndmask_b32_e32 v1, v1, v17, vcc
	v_sqrt_f32_e32 v17, v1
	s_nop 0
	v_add_u32_e32 v18, -1, v17
	v_fma_f32 v19, -v18, v17, v1
	v_cmp_ge_f32_e64 s[0:1], 0, v19
	v_add_u32_e32 v19, 1, v17
	s_nop 0
	v_cndmask_b32_e64 v18, v17, v18, s[0:1]
	v_fma_f32 v17, -v19, v17, v1
	v_cmp_lt_f32_e64 s[0:1], 0, v17
	s_nop 1
	v_cndmask_b32_e64 v17, v18, v19, s[0:1]
	v_mul_f32_e32 v18, 0x37800000, v17
	v_cndmask_b32_e32 v17, v17, v18, vcc
	v_cmp_class_f32_e32 vcc, v1, v160
	s_nop 1
	v_cndmask_b32_e32 v1, v17, v1, vcc
	ds_read_b32 v17, v81 offset:9984
	s_waitcnt lgkmcnt(0)
	v_mul_f32_e32 v2, v2, v17
	v_mul_f32_e32 v1, v2, v1
	ds_write2st64_b32 v81, v3, v1 offset0:175 offset1:239
	v_add_f32_e32 v1, v88, v20
	v_mul_f32_e32 v1, 0xbfb8aa3b, v1
	v_exp_f32_e32 v1, v1
	s_nop 0
	v_add_f32_e32 v1, 1.0, v1
	s_nop 0
	v_rcp_f32_e32 v1, v1
	s_nop 0
	v_mul_f32_e32 v1, 0xc1000000, v1
	v_mul_f32_e32 v2, v1, v16
	v_fmamk_f32 v1, v2, 0x3ab60b61, v158
	v_fmaak_f32 v1, v2, v1, 0x3d2aaaab
	v_fmaak_f32 v1, v2, v1, 0x3e2aaaab
	v_fma_f32 v1, v2, v1, 0.5
	v_fma_f32 v1, v2, v1, 1.0
	v_mul_f32_e32 v1, v2, v1
	v_cmp_gt_f32_e32 vcc, s95, v2
	s_and_saveexec_b64 s[0:1], vcc
	s_cbranch_execz .LBB0_266
	v_mul_f32_e32 v1, 0x3fb8aa3b, v2
	v_rndne_f32_e32 v1, v1
	v_fmamk_f32 v3, v1, 0xbf317218, v2
	v_fmac_f32_e32 v3, 0x3102e308, v1
	v_fmamk_f32 v17, v3, 0x395133b1, v159
	v_cmp_eq_f32_e32 vcc, s96, v1
	v_cvt_i32_f32_e32 v1, v1
	v_fmaak_f32 v17, v3, v17, 0x3c0887f9
	v_fmaak_f32 v17, v3, v17, 0x3d2aaa81
	v_fmaak_f32 v17, v3, v17, 0x3e2aaaab
	v_fma_f32 v17, v3, v17, 0.5
	v_ldexp_f32 v1, 1.0, v1
	v_mul_f32_e32 v17, v3, v17
	v_cndmask_b32_e32 v1, v1, v171, vcc
	v_fmac_f32_e32 v3, v3, v17
	v_add_f32_e32 v17, -1.0, v1
	v_fmac_f32_e32 v17, v1, v3
	v_add_f32_e32 v1, v17, v17
	v_cndmask_b32_e32 v1, v17, v1, vcc
	v_cmp_ngt_f32_e32 vcc, s97, v2
	s_nop 1
	v_cndmask_b32_e32 v1, -1.0, v1, vcc
.LBB0_266:
	s_or_b64 exec, exec, s[0:1]
	v_add_f32_e32 v2, v86, v4
	v_mul_f32_e32 v2, 0xbfb8aa3b, v2
	v_exp_f32_e32 v2, v2
	s_nop 0
	v_add_f32_e32 v2, 1.0, v2
	s_nop 0
	v_add_f32_e32 v4, 2.0, v1
	v_rcp_f32_e32 v2, v2
	s_nop 0
	v_add_f32_e32 v3, 1.0, v1
	v_mul_f32_e64 v1, v4, -v1
	v_cmp_gt_f32_e32 vcc, s28, v1
	v_mul_f32_e32 v4, 0x4f800000, v1
	s_nop 0
	v_cndmask_b32_e32 v1, v1, v4, vcc
	v_sqrt_f32_e32 v4, v1
	s_nop 0
	v_add_u32_e32 v17, -1, v4
	v_fma_f32 v18, -v17, v4, v1
	v_cmp_ge_f32_e64 s[0:1], 0, v18
	v_add_u32_e32 v18, 1, v4
	s_nop 0
	v_cndmask_b32_e64 v17, v4, v17, s[0:1]
	v_fma_f32 v4, -v18, v4, v1
	v_cmp_lt_f32_e64 s[0:1], 0, v4
	s_nop 1
	v_cndmask_b32_e64 v4, v17, v18, s[0:1]
	v_mul_f32_e32 v17, 0x37800000, v4
	v_cndmask_b32_e32 v4, v4, v17, vcc
	v_cmp_class_f32_e32 vcc, v1, v160
	s_nop 1
	v_cndmask_b32_e32 v1, v4, v1, vcc
	ds_read_b32 v4, v81 offset:11264
	s_waitcnt lgkmcnt(0)
	v_mul_f32_e32 v2, v2, v4
	v_mul_f32_e32 v1, v2, v1
	ds_write2st64_b32 v81, v3, v1 offset0:180 offset1:244
	v_add_f32_e32 v1, v88, v21
	v_mul_f32_e32 v1, 0xbfb8aa3b, v1
	v_exp_f32_e32 v1, v1
	s_nop 0
	v_add_f32_e32 v1, 1.0, v1
	s_nop 0
	v_rcp_f32_e32 v1, v1
	s_nop 0
	v_mul_f32_e32 v1, 0xc1000000, v1
	v_mul_f32_e32 v2, v1, v16
	v_fmamk_f32 v1, v2, 0x3ab60b61, v158
	v_fmaak_f32 v1, v2, v1, 0x3d2aaaab
	v_fmaak_f32 v1, v2, v1, 0x3e2aaaab
	v_fma_f32 v1, v2, v1, 0.5
	v_fma_f32 v1, v2, v1, 1.0
	v_mul_f32_e32 v1, v2, v1
	v_cmp_gt_f32_e32 vcc, s95, v2
	s_and_saveexec_b64 s[0:1], vcc
	s_cbranch_execz .LBB0_268
	v_mul_f32_e32 v1, 0x3fb8aa3b, v2
	v_rndne_f32_e32 v1, v1
	v_fmamk_f32 v3, v1, 0xbf317218, v2
	v_fmac_f32_e32 v3, 0x3102e308, v1
	v_fmamk_f32 v4, v3, 0x395133b1, v159
	v_cmp_eq_f32_e32 vcc, s96, v1
	v_cvt_i32_f32_e32 v1, v1
	v_fmaak_f32 v4, v3, v4, 0x3c0887f9
	v_fmaak_f32 v4, v3, v4, 0x3d2aaa81
	v_fmaak_f32 v4, v3, v4, 0x3e2aaaab
	v_fma_f32 v4, v3, v4, 0.5
	v_ldexp_f32 v1, 1.0, v1
	v_mul_f32_e32 v4, v3, v4
	v_cndmask_b32_e32 v1, v1, v171, vcc
	v_fmac_f32_e32 v3, v3, v4
	v_add_f32_e32 v4, -1.0, v1
	v_fmac_f32_e32 v4, v1, v3
	v_add_f32_e32 v1, v4, v4
	v_cndmask_b32_e32 v1, v4, v1, vcc
	v_cmp_ngt_f32_e32 vcc, s97, v2
	s_nop 1
	v_cndmask_b32_e32 v1, -1.0, v1, vcc
.LBB0_268:
	s_or_b64 exec, exec, s[0:1]
	v_add_f32_e32 v2, v86, v5
	v_mul_f32_e32 v2, 0xbfb8aa3b, v2
	v_exp_f32_e32 v2, v2
	s_nop 0
	v_add_f32_e32 v2, 1.0, v2
	s_nop 0
	v_add_f32_e32 v4, 2.0, v1
	v_rcp_f32_e32 v2, v2
	s_nop 0
	v_add_f32_e32 v3, 1.0, v1
	v_mul_f32_e64 v1, v4, -v1
	v_cmp_gt_f32_e32 vcc, s28, v1
	v_mul_f32_e32 v4, 0x4f800000, v1
	s_nop 0
	v_cndmask_b32_e32 v1, v1, v4, vcc
	v_sqrt_f32_e32 v4, v1
	s_nop 0
	v_add_u32_e32 v5, -1, v4
	v_fma_f32 v17, -v5, v4, v1
	v_cmp_ge_f32_e64 s[0:1], 0, v17
	v_add_u32_e32 v17, 1, v4
	s_nop 0
	v_cndmask_b32_e64 v5, v4, v5, s[0:1]
	v_fma_f32 v4, -v17, v4, v1
	v_cmp_lt_f32_e64 s[0:1], 0, v4
	s_nop 1
	v_cndmask_b32_e64 v4, v5, v17, s[0:1]
	v_mul_f32_e32 v5, 0x37800000, v4
	v_cndmask_b32_e32 v4, v4, v5, vcc
	v_cmp_class_f32_e32 vcc, v1, v160
	s_nop 1
	v_cndmask_b32_e32 v1, v4, v1, vcc
	ds_read_b32 v4, v81 offset:11520
	s_waitcnt lgkmcnt(0)
	v_mul_f32_e32 v2, v2, v4
	v_mul_f32_e32 v1, v2, v1
	ds_write2st64_b32 v81, v3, v1 offset0:181 offset1:245
	v_add_f32_e32 v1, v88, v22
	v_mul_f32_e32 v1, 0xbfb8aa3b, v1
	v_exp_f32_e32 v1, v1
	s_nop 0
	v_add_f32_e32 v1, 1.0, v1
	s_nop 0
	v_rcp_f32_e32 v1, v1
	s_nop 0
	v_mul_f32_e32 v1, 0xc1000000, v1
	v_mul_f32_e32 v2, v1, v16
	v_fmamk_f32 v1, v2, 0x3ab60b61, v158
	v_fmaak_f32 v1, v2, v1, 0x3d2aaaab
	v_fmaak_f32 v1, v2, v1, 0x3e2aaaab
	v_fma_f32 v1, v2, v1, 0.5
	v_fma_f32 v1, v2, v1, 1.0
	v_mul_f32_e32 v1, v2, v1
	v_cmp_gt_f32_e32 vcc, s95, v2
	s_and_saveexec_b64 s[0:1], vcc
	s_cbranch_execz .LBB0_270
	v_mul_f32_e32 v1, 0x3fb8aa3b, v2
	v_rndne_f32_e32 v1, v1
	v_fmamk_f32 v3, v1, 0xbf317218, v2
	v_fmac_f32_e32 v3, 0x3102e308, v1
	v_fmamk_f32 v4, v3, 0x395133b1, v159
	v_cmp_eq_f32_e32 vcc, s96, v1
	v_cvt_i32_f32_e32 v1, v1
	v_fmaak_f32 v4, v3, v4, 0x3c0887f9
	v_fmaak_f32 v4, v3, v4, 0x3d2aaa81
	v_fmaak_f32 v4, v3, v4, 0x3e2aaaab
	v_fma_f32 v4, v3, v4, 0.5
	v_ldexp_f32 v1, 1.0, v1
	v_mul_f32_e32 v4, v3, v4
	v_cndmask_b32_e32 v1, v1, v171, vcc
	v_fmac_f32_e32 v3, v3, v4
	v_add_f32_e32 v4, -1.0, v1
	v_fmac_f32_e32 v4, v1, v3
	v_add_f32_e32 v1, v4, v4
	v_cndmask_b32_e32 v1, v4, v1, vcc
	v_cmp_ngt_f32_e32 vcc, s97, v2
	s_nop 1
	v_cndmask_b32_e32 v1, -1.0, v1, vcc
.LBB0_270:
	s_or_b64 exec, exec, s[0:1]
	v_add_f32_e32 v2, v86, v6
	v_mul_f32_e32 v2, 0xbfb8aa3b, v2
	v_exp_f32_e32 v2, v2
	s_nop 0
	v_add_f32_e32 v2, 1.0, v2
	s_nop 0
	v_add_f32_e32 v4, 2.0, v1
	v_rcp_f32_e32 v2, v2
	s_nop 0
	v_add_f32_e32 v3, 1.0, v1
	v_mul_f32_e64 v1, v4, -v1
	v_cmp_gt_f32_e32 vcc, s28, v1
	v_mul_f32_e32 v4, 0x4f800000, v1
	s_nop 0
	v_cndmask_b32_e32 v1, v1, v4, vcc
	v_sqrt_f32_e32 v4, v1
	s_nop 0
	v_add_u32_e32 v5, -1, v4
	v_fma_f32 v6, -v5, v4, v1
	v_cmp_ge_f32_e64 s[0:1], 0, v6
	v_add_u32_e32 v6, 1, v4
	s_nop 0
	v_cndmask_b32_e64 v5, v4, v5, s[0:1]
	v_fma_f32 v4, -v6, v4, v1
	v_cmp_lt_f32_e64 s[0:1], 0, v4
	s_nop 1
	v_cndmask_b32_e64 v4, v5, v6, s[0:1]
	v_mul_f32_e32 v5, 0x37800000, v4
	v_cndmask_b32_e32 v4, v4, v5, vcc
	v_cmp_class_f32_e32 vcc, v1, v160
	s_nop 1
	v_cndmask_b32_e32 v1, v4, v1, vcc
	ds_read_b32 v4, v81 offset:11776
	s_waitcnt lgkmcnt(0)
	v_mul_f32_e32 v2, v2, v4
	v_mul_f32_e32 v1, v2, v1
	ds_write2st64_b32 v81, v3, v1 offset0:182 offset1:246
	v_add_f32_e32 v1, v88, v23
	v_mul_f32_e32 v1, 0xbfb8aa3b, v1
	v_exp_f32_e32 v1, v1
	s_nop 0
	v_add_f32_e32 v1, 1.0, v1
	s_nop 0
	v_rcp_f32_e32 v1, v1
	s_nop 0
	v_mul_f32_e32 v1, 0xc1000000, v1
	v_mul_f32_e32 v2, v1, v16
	v_fmamk_f32 v1, v2, 0x3ab60b61, v158
	v_fmaak_f32 v1, v2, v1, 0x3d2aaaab
	v_fmaak_f32 v1, v2, v1, 0x3e2aaaab
	v_fma_f32 v1, v2, v1, 0.5
	v_fma_f32 v1, v2, v1, 1.0
	v_mul_f32_e32 v1, v2, v1
	v_cmp_gt_f32_e32 vcc, s95, v2
	s_and_saveexec_b64 s[0:1], vcc
	s_cbranch_execz .LBB0_272
	v_mul_f32_e32 v1, 0x3fb8aa3b, v2
	v_rndne_f32_e32 v1, v1
	v_fmamk_f32 v3, v1, 0xbf317218, v2
	v_fmac_f32_e32 v3, 0x3102e308, v1
	v_fmamk_f32 v4, v3, 0x395133b1, v159
	v_cmp_eq_f32_e32 vcc, s96, v1
	v_cvt_i32_f32_e32 v1, v1
	v_fmaak_f32 v4, v3, v4, 0x3c0887f9
	v_fmaak_f32 v4, v3, v4, 0x3d2aaa81
	v_fmaak_f32 v4, v3, v4, 0x3e2aaaab
	v_fma_f32 v4, v3, v4, 0.5
	v_ldexp_f32 v1, 1.0, v1
	v_mul_f32_e32 v4, v3, v4
	v_cndmask_b32_e32 v1, v1, v171, vcc
	v_fmac_f32_e32 v3, v3, v4
	v_add_f32_e32 v4, -1.0, v1
	v_fmac_f32_e32 v4, v1, v3
	v_add_f32_e32 v1, v4, v4
	v_cndmask_b32_e32 v1, v4, v1, vcc
	v_cmp_ngt_f32_e32 vcc, s97, v2
	s_nop 1
	v_cndmask_b32_e32 v1, -1.0, v1, vcc
.LBB0_272:
	s_or_b64 exec, exec, s[0:1]
	v_add_f32_e32 v2, v86, v7
	v_mul_f32_e32 v2, 0xbfb8aa3b, v2
	v_exp_f32_e32 v2, v2
	s_nop 0
	v_add_f32_e32 v2, 1.0, v2
	s_nop 0
	v_add_f32_e32 v4, 2.0, v1
	v_rcp_f32_e32 v2, v2
	s_nop 0
	v_add_f32_e32 v3, 1.0, v1
	v_mul_f32_e64 v1, v4, -v1
	v_cmp_gt_f32_e32 vcc, s28, v1
	v_mul_f32_e32 v4, 0x4f800000, v1
	s_nop 0
	v_cndmask_b32_e32 v1, v1, v4, vcc
	v_sqrt_f32_e32 v4, v1
	s_nop 0
	v_add_u32_e32 v5, -1, v4
	v_fma_f32 v6, -v5, v4, v1
	v_cmp_ge_f32_e64 s[0:1], 0, v6
	v_add_u32_e32 v6, 1, v4
	s_nop 0
	v_cndmask_b32_e64 v5, v4, v5, s[0:1]
	v_fma_f32 v4, -v6, v4, v1
	v_cmp_lt_f32_e64 s[0:1], 0, v4
	s_nop 1
	v_cndmask_b32_e64 v4, v5, v6, s[0:1]
	v_mul_f32_e32 v5, 0x37800000, v4
	v_cndmask_b32_e32 v4, v4, v5, vcc
	v_cmp_class_f32_e32 vcc, v1, v160
	s_nop 1
	v_cndmask_b32_e32 v1, v4, v1, vcc
	ds_read_b32 v4, v81 offset:12032
	s_waitcnt lgkmcnt(0)
	v_mul_f32_e32 v2, v2, v4
	v_mul_f32_e32 v1, v2, v1
	ds_write2st64_b32 v81, v3, v1 offset0:183 offset1:247
	v_add_f32_e32 v1, v88, v24
	v_mul_f32_e32 v1, 0xbfb8aa3b, v1
	v_exp_f32_e32 v1, v1
	s_nop 0
	v_add_f32_e32 v1, 1.0, v1
	s_nop 0
	v_rcp_f32_e32 v1, v1
	s_nop 0
	v_mul_f32_e32 v1, 0xc1000000, v1
	v_mul_f32_e32 v2, v1, v16
	v_fmamk_f32 v1, v2, 0x3ab60b61, v158
	v_fmaak_f32 v1, v2, v1, 0x3d2aaaab
	v_fmaak_f32 v1, v2, v1, 0x3e2aaaab
	v_fma_f32 v1, v2, v1, 0.5
	v_fma_f32 v1, v2, v1, 1.0
	v_mul_f32_e32 v1, v2, v1
	v_cmp_gt_f32_e32 vcc, s95, v2
	s_and_saveexec_b64 s[0:1], vcc
	s_cbranch_execz .LBB0_274
	v_mul_f32_e32 v1, 0x3fb8aa3b, v2
	v_rndne_f32_e32 v1, v1
	v_fmamk_f32 v3, v1, 0xbf317218, v2
	v_fmac_f32_e32 v3, 0x3102e308, v1
	v_fmamk_f32 v4, v3, 0x395133b1, v159
	v_cmp_eq_f32_e32 vcc, s96, v1
	v_cvt_i32_f32_e32 v1, v1
	v_fmaak_f32 v4, v3, v4, 0x3c0887f9
	v_fmaak_f32 v4, v3, v4, 0x3d2aaa81
	v_fmaak_f32 v4, v3, v4, 0x3e2aaaab
	v_fma_f32 v4, v3, v4, 0.5
	v_ldexp_f32 v1, 1.0, v1
	v_mul_f32_e32 v4, v3, v4
	v_cndmask_b32_e32 v1, v1, v171, vcc
	v_fmac_f32_e32 v3, v3, v4
	v_add_f32_e32 v4, -1.0, v1
	v_fmac_f32_e32 v4, v1, v3
	v_add_f32_e32 v1, v4, v4
	v_cndmask_b32_e32 v1, v4, v1, vcc
	v_cmp_ngt_f32_e32 vcc, s97, v2
	s_nop 1
	v_cndmask_b32_e32 v1, -1.0, v1, vcc
.LBB0_274:
	s_or_b64 exec, exec, s[0:1]
	v_add_f32_e32 v2, v86, v8
	v_mul_f32_e32 v2, 0xbfb8aa3b, v2
	v_exp_f32_e32 v2, v2
	s_nop 0
	v_add_f32_e32 v2, 1.0, v2
	s_nop 0
	v_add_f32_e32 v4, 2.0, v1
	v_rcp_f32_e32 v2, v2
	s_nop 0
	v_add_f32_e32 v3, 1.0, v1
	v_mul_f32_e64 v1, v4, -v1
	v_cmp_gt_f32_e32 vcc, s28, v1
	v_mul_f32_e32 v4, 0x4f800000, v1
	s_nop 0
	v_cndmask_b32_e32 v1, v1, v4, vcc
	v_sqrt_f32_e32 v4, v1
	s_nop 0
	v_add_u32_e32 v5, -1, v4
	v_fma_f32 v6, -v5, v4, v1
	v_cmp_ge_f32_e64 s[0:1], 0, v6
	v_add_u32_e32 v6, 1, v4
	s_nop 0
	v_cndmask_b32_e64 v5, v4, v5, s[0:1]
	v_fma_f32 v4, -v6, v4, v1
	v_cmp_lt_f32_e64 s[0:1], 0, v4
	s_nop 1
	v_cndmask_b32_e64 v4, v5, v6, s[0:1]
	v_mul_f32_e32 v5, 0x37800000, v4
	v_cndmask_b32_e32 v4, v4, v5, vcc
	v_cmp_class_f32_e32 vcc, v1, v160
	s_nop 1
	v_cndmask_b32_e32 v1, v4, v1, vcc
	ds_read_b32 v4, v81 offset:13312
	s_waitcnt lgkmcnt(0)
	v_mul_f32_e32 v2, v2, v4
	v_mul_f32_e32 v1, v2, v1
	ds_write2st64_b32 v81, v3, v1 offset0:188 offset1:252
	v_add_f32_e32 v1, v88, v25
	v_mul_f32_e32 v1, 0xbfb8aa3b, v1
	v_exp_f32_e32 v1, v1
	s_nop 0
	v_add_f32_e32 v1, 1.0, v1
	s_nop 0
	v_rcp_f32_e32 v1, v1
	s_nop 0
	v_mul_f32_e32 v1, 0xc1000000, v1
	v_mul_f32_e32 v2, v1, v16
	v_fmamk_f32 v1, v2, 0x3ab60b61, v158
	v_fmaak_f32 v1, v2, v1, 0x3d2aaaab
	v_fmaak_f32 v1, v2, v1, 0x3e2aaaab
	v_fma_f32 v1, v2, v1, 0.5
	v_fma_f32 v1, v2, v1, 1.0
	v_mul_f32_e32 v1, v2, v1
	v_cmp_gt_f32_e32 vcc, s95, v2
	s_and_saveexec_b64 s[0:1], vcc
	s_cbranch_execz .LBB0_276
	v_mul_f32_e32 v1, 0x3fb8aa3b, v2
	v_rndne_f32_e32 v1, v1
	v_fmamk_f32 v3, v1, 0xbf317218, v2
	v_fmac_f32_e32 v3, 0x3102e308, v1
	v_fmamk_f32 v4, v3, 0x395133b1, v159
	v_cmp_eq_f32_e32 vcc, s96, v1
	v_cvt_i32_f32_e32 v1, v1
	v_fmaak_f32 v4, v3, v4, 0x3c0887f9
	v_fmaak_f32 v4, v3, v4, 0x3d2aaa81
	v_fmaak_f32 v4, v3, v4, 0x3e2aaaab
	v_fma_f32 v4, v3, v4, 0.5
	v_ldexp_f32 v1, 1.0, v1
	v_mul_f32_e32 v4, v3, v4
	v_cndmask_b32_e32 v1, v1, v171, vcc
	v_fmac_f32_e32 v3, v3, v4
	v_add_f32_e32 v4, -1.0, v1
	v_fmac_f32_e32 v4, v1, v3
	v_add_f32_e32 v1, v4, v4
	v_cndmask_b32_e32 v1, v4, v1, vcc
	v_cmp_ngt_f32_e32 vcc, s97, v2
	s_nop 1
	v_cndmask_b32_e32 v1, -1.0, v1, vcc
.LBB0_276:
	s_or_b64 exec, exec, s[0:1]
	v_add_f32_e32 v2, v86, v9
	v_mul_f32_e32 v2, 0xbfb8aa3b, v2
	v_exp_f32_e32 v2, v2
	s_nop 0
	v_add_f32_e32 v2, 1.0, v2
	s_nop 0
	v_add_f32_e32 v4, 2.0, v1
	v_rcp_f32_e32 v2, v2
	s_nop 0
	v_add_f32_e32 v3, 1.0, v1
	v_mul_f32_e64 v1, v4, -v1
	v_cmp_gt_f32_e32 vcc, s28, v1
	v_mul_f32_e32 v4, 0x4f800000, v1
	s_nop 0
	v_cndmask_b32_e32 v1, v1, v4, vcc
	v_sqrt_f32_e32 v4, v1
	s_nop 0
	v_add_u32_e32 v5, -1, v4
	v_fma_f32 v6, -v5, v4, v1
	v_cmp_ge_f32_e64 s[0:1], 0, v6
	v_add_u32_e32 v6, 1, v4
	s_nop 0
	v_cndmask_b32_e64 v5, v4, v5, s[0:1]
	v_fma_f32 v4, -v6, v4, v1
	v_cmp_lt_f32_e64 s[0:1], 0, v4
	s_nop 1
	v_cndmask_b32_e64 v4, v5, v6, s[0:1]
	v_mul_f32_e32 v5, 0x37800000, v4
	v_cndmask_b32_e32 v4, v4, v5, vcc
	v_cmp_class_f32_e32 vcc, v1, v160
	s_nop 1
	v_cndmask_b32_e32 v1, v4, v1, vcc
	ds_read_b32 v4, v81 offset:13568
	s_waitcnt lgkmcnt(0)
	v_mul_f32_e32 v2, v2, v4
	v_mul_f32_e32 v1, v2, v1
	ds_write2st64_b32 v81, v3, v1 offset0:189 offset1:253
	v_add_f32_e32 v1, v88, v26
	v_mul_f32_e32 v1, 0xbfb8aa3b, v1
	v_exp_f32_e32 v1, v1
	s_nop 0
	v_add_f32_e32 v1, 1.0, v1
	s_nop 0
	v_rcp_f32_e32 v1, v1
	s_nop 0
	v_mul_f32_e32 v1, 0xc1000000, v1
	v_mul_f32_e32 v2, v1, v16
	v_fmamk_f32 v1, v2, 0x3ab60b61, v158
	v_fmaak_f32 v1, v2, v1, 0x3d2aaaab
	v_fmaak_f32 v1, v2, v1, 0x3e2aaaab
	v_fma_f32 v1, v2, v1, 0.5
	v_fma_f32 v1, v2, v1, 1.0
	v_mul_f32_e32 v1, v2, v1
	v_cmp_gt_f32_e32 vcc, s95, v2
	s_and_saveexec_b64 s[0:1], vcc
	s_cbranch_execz .LBB0_278
	v_mul_f32_e32 v1, 0x3fb8aa3b, v2
	v_rndne_f32_e32 v1, v1
	v_fmamk_f32 v3, v1, 0xbf317218, v2
	v_fmac_f32_e32 v3, 0x3102e308, v1
	v_fmamk_f32 v4, v3, 0x395133b1, v159
	v_cmp_eq_f32_e32 vcc, s96, v1
	v_cvt_i32_f32_e32 v1, v1
	v_fmaak_f32 v4, v3, v4, 0x3c0887f9
	v_fmaak_f32 v4, v3, v4, 0x3d2aaa81
	v_fmaak_f32 v4, v3, v4, 0x3e2aaaab
	v_fma_f32 v4, v3, v4, 0.5
	v_ldexp_f32 v1, 1.0, v1
	v_mul_f32_e32 v4, v3, v4
	v_cndmask_b32_e32 v1, v1, v171, vcc
	v_fmac_f32_e32 v3, v3, v4
	v_add_f32_e32 v4, -1.0, v1
	v_fmac_f32_e32 v4, v1, v3
	v_add_f32_e32 v1, v4, v4
	v_cndmask_b32_e32 v1, v4, v1, vcc
	v_cmp_ngt_f32_e32 vcc, s97, v2
	s_nop 1
	v_cndmask_b32_e32 v1, -1.0, v1, vcc
.LBB0_278:
	s_or_b64 exec, exec, s[0:1]
	v_add_f32_e32 v2, v86, v10
	v_mul_f32_e32 v2, 0xbfb8aa3b, v2
	v_exp_f32_e32 v2, v2
	s_nop 0
	v_add_f32_e32 v2, 1.0, v2
	s_nop 0
	v_add_f32_e32 v4, 2.0, v1
	v_rcp_f32_e32 v2, v2
	s_nop 0
	v_add_f32_e32 v3, 1.0, v1
	v_mul_f32_e64 v1, v4, -v1
	v_cmp_gt_f32_e32 vcc, s28, v1
	v_mul_f32_e32 v4, 0x4f800000, v1
	s_nop 0
	v_cndmask_b32_e32 v1, v1, v4, vcc
	v_sqrt_f32_e32 v4, v1
	s_nop 0
	v_add_u32_e32 v5, -1, v4
	v_fma_f32 v6, -v5, v4, v1
	v_cmp_ge_f32_e64 s[0:1], 0, v6
	v_add_u32_e32 v6, 1, v4
	s_nop 0
	v_cndmask_b32_e64 v5, v4, v5, s[0:1]
	v_fma_f32 v4, -v6, v4, v1
	v_cmp_lt_f32_e64 s[0:1], 0, v4
	s_nop 1
	v_cndmask_b32_e64 v4, v5, v6, s[0:1]
	v_mul_f32_e32 v5, 0x37800000, v4
	v_cndmask_b32_e32 v4, v4, v5, vcc
	v_cmp_class_f32_e32 vcc, v1, v160
	s_nop 1
	v_cndmask_b32_e32 v1, v4, v1, vcc
	ds_read_b32 v4, v81 offset:13824
	s_waitcnt lgkmcnt(0)
	v_mul_f32_e32 v2, v2, v4
	v_mul_f32_e32 v1, v2, v1
	ds_write2st64_b32 v81, v3, v1 offset0:190 offset1:254
	v_add_f32_e32 v1, v88, v27
	v_mul_f32_e32 v1, 0xbfb8aa3b, v1
	v_exp_f32_e32 v1, v1
	s_nop 0
	v_add_f32_e32 v1, 1.0, v1
	s_nop 0
	v_rcp_f32_e32 v1, v1
	s_nop 0
	v_mul_f32_e32 v1, 0xc1000000, v1
	v_mul_f32_e32 v2, v1, v16
	v_fmamk_f32 v1, v2, 0x3ab60b61, v158
	v_fmaak_f32 v1, v2, v1, 0x3d2aaaab
	v_fmaak_f32 v1, v2, v1, 0x3e2aaaab
	v_fma_f32 v1, v2, v1, 0.5
	v_fma_f32 v1, v2, v1, 1.0
	v_mul_f32_e32 v1, v2, v1
	v_cmp_gt_f32_e32 vcc, s95, v2
	s_and_saveexec_b64 s[0:1], vcc
	s_cbranch_execz .LBB0_280
	v_mul_f32_e32 v1, 0x3fb8aa3b, v2
	v_rndne_f32_e32 v1, v1
	v_fmamk_f32 v3, v1, 0xbf317218, v2
	v_fmac_f32_e32 v3, 0x3102e308, v1
	v_fmamk_f32 v4, v3, 0x395133b1, v159
	v_cmp_eq_f32_e32 vcc, s96, v1
	v_cvt_i32_f32_e32 v1, v1
	v_fmaak_f32 v4, v3, v4, 0x3c0887f9
	v_fmaak_f32 v4, v3, v4, 0x3d2aaa81
	v_fmaak_f32 v4, v3, v4, 0x3e2aaaab
	v_fma_f32 v4, v3, v4, 0.5
	v_ldexp_f32 v1, 1.0, v1
	v_mul_f32_e32 v4, v3, v4
	v_cndmask_b32_e32 v1, v1, v171, vcc
	v_fmac_f32_e32 v3, v3, v4
	v_add_f32_e32 v4, -1.0, v1
	v_fmac_f32_e32 v4, v1, v3
	v_add_f32_e32 v1, v4, v4
	v_cndmask_b32_e32 v1, v4, v1, vcc
	v_cmp_ngt_f32_e32 vcc, s97, v2
	s_nop 1
	v_cndmask_b32_e32 v1, -1.0, v1, vcc
.LBB0_280:
	s_or_b64 exec, exec, s[0:1]
	v_add_f32_e32 v2, v86, v11
	v_mul_f32_e32 v2, 0xbfb8aa3b, v2
	v_exp_f32_e32 v2, v2
	s_nop 0
	v_add_f32_e32 v2, 1.0, v2
	s_nop 0
	v_add_f32_e32 v4, 2.0, v1
	v_rcp_f32_e32 v2, v2
	s_nop 0
	v_add_f32_e32 v3, 1.0, v1
	v_mul_f32_e64 v1, v4, -v1
	v_cmp_gt_f32_e32 vcc, s28, v1
	v_mul_f32_e32 v4, 0x4f800000, v1
	s_nop 0
	v_cndmask_b32_e32 v1, v1, v4, vcc
	v_sqrt_f32_e32 v4, v1
	s_nop 0
	v_add_u32_e32 v5, -1, v4
	v_fma_f32 v6, -v5, v4, v1
	v_cmp_ge_f32_e64 s[0:1], 0, v6
	v_add_u32_e32 v6, 1, v4
	s_nop 0
	v_cndmask_b32_e64 v5, v4, v5, s[0:1]
	v_fma_f32 v4, -v6, v4, v1
	v_cmp_lt_f32_e64 s[0:1], 0, v4
	s_nop 1
	v_cndmask_b32_e64 v4, v5, v6, s[0:1]
	v_mul_f32_e32 v5, 0x37800000, v4
	v_cndmask_b32_e32 v4, v4, v5, vcc
	v_cmp_class_f32_e32 vcc, v1, v160
	s_nop 1
	v_cndmask_b32_e32 v1, v4, v1, vcc
	ds_read_b32 v4, v81 offset:14080
	s_waitcnt lgkmcnt(0)
	v_mul_f32_e32 v2, v2, v4
	v_mul_f32_e32 v1, v2, v1
	ds_write2st64_b32 v81, v3, v1 offset0:191 offset1:255
	v_add_f32_e32 v1, v88, v28
	v_mul_f32_e32 v1, 0xbfb8aa3b, v1
	v_exp_f32_e32 v1, v1
	s_nop 0
	v_add_f32_e32 v1, 1.0, v1
	s_nop 0
	v_rcp_f32_e32 v1, v1
	s_nop 0
	v_mul_f32_e32 v1, 0xc1000000, v1
	v_mul_f32_e32 v2, v1, v16
	v_fmamk_f32 v1, v2, 0x3ab60b61, v158
	v_fmaak_f32 v1, v2, v1, 0x3d2aaaab
	v_fmaak_f32 v1, v2, v1, 0x3e2aaaab
	v_fma_f32 v1, v2, v1, 0.5
	v_fma_f32 v1, v2, v1, 1.0
	v_mul_f32_e32 v1, v2, v1
	v_cmp_gt_f32_e32 vcc, s95, v2
	s_and_saveexec_b64 s[0:1], vcc
	s_cbranch_execz .LBB0_282
	v_mul_f32_e32 v1, 0x3fb8aa3b, v2
	v_rndne_f32_e32 v1, v1
	v_fmamk_f32 v3, v1, 0xbf317218, v2
	v_fmac_f32_e32 v3, 0x3102e308, v1
	v_fmamk_f32 v4, v3, 0x395133b1, v159
	v_cmp_eq_f32_e32 vcc, s96, v1
	v_cvt_i32_f32_e32 v1, v1
	v_fmaak_f32 v4, v3, v4, 0x3c0887f9
	v_fmaak_f32 v4, v3, v4, 0x3d2aaa81
	v_fmaak_f32 v4, v3, v4, 0x3e2aaaab
	v_fma_f32 v4, v3, v4, 0.5
	v_ldexp_f32 v1, 1.0, v1
	v_mul_f32_e32 v4, v3, v4
	v_cndmask_b32_e32 v1, v1, v171, vcc
	v_fmac_f32_e32 v3, v3, v4
	v_add_f32_e32 v4, -1.0, v1
	v_fmac_f32_e32 v4, v1, v3
	v_add_f32_e32 v1, v4, v4
	v_cndmask_b32_e32 v1, v4, v1, vcc
	v_cmp_ngt_f32_e32 vcc, s97, v2
	s_nop 1
	v_cndmask_b32_e32 v1, -1.0, v1, vcc
.LBB0_282:
	s_or_b64 exec, exec, s[0:1]
	v_add_f32_e32 v2, v86, v12
	v_mul_f32_e32 v2, 0xbfb8aa3b, v2
	v_exp_f32_e32 v2, v2
	v_lshl_add_u32 v95, v0, 2, v172
	v_add_f32_e32 v2, 1.0, v2
	s_nop 0
	v_add_f32_e32 v4, 2.0, v1
	v_rcp_f32_e32 v2, v2
	s_nop 0
	v_add_f32_e32 v3, 1.0, v1
	v_mul_f32_e64 v1, v4, -v1
	v_cmp_gt_f32_e32 vcc, s28, v1
	v_mul_f32_e32 v4, 0x4f800000, v1
	ds_write_b32 v81, v3 offset:50176
	v_cndmask_b32_e32 v1, v1, v4, vcc
	v_sqrt_f32_e32 v4, v1
	s_nop 0
	v_add_u32_e32 v5, -1, v4
	v_fma_f32 v6, -v5, v4, v1
	v_cmp_ge_f32_e64 s[0:1], 0, v6
	v_add_u32_e32 v6, 1, v4
	s_nop 0
	v_cndmask_b32_e64 v5, v4, v5, s[0:1]
	v_fma_f32 v4, -v6, v4, v1
	v_cmp_lt_f32_e64 s[0:1], 0, v4
	s_nop 1
	v_cndmask_b32_e64 v4, v5, v6, s[0:1]
	v_mul_f32_e32 v5, 0x37800000, v4
	v_cndmask_b32_e32 v4, v4, v5, vcc
	v_cmp_class_f32_e32 vcc, v1, v160
	s_nop 1
	v_cndmask_b32_e32 v1, v4, v1, vcc
	ds_read_b32 v4, v81 offset:15360
	s_waitcnt lgkmcnt(0)
	v_mul_f32_e32 v2, v2, v4
	v_mul_f32_e32 v1, v2, v1
	ds_write_b32 v95, v1
	v_add_f32_e32 v1, v88, v29
	v_mul_f32_e32 v1, 0xbfb8aa3b, v1
	v_exp_f32_e32 v1, v1
	s_nop 0
	v_add_f32_e32 v1, 1.0, v1
	s_nop 0
	v_rcp_f32_e32 v1, v1
	s_nop 0
	v_mul_f32_e32 v1, 0xc1000000, v1
	v_mul_f32_e32 v2, v1, v16
	v_fmamk_f32 v1, v2, 0x3ab60b61, v158
	v_fmaak_f32 v1, v2, v1, 0x3d2aaaab
	v_fmaak_f32 v1, v2, v1, 0x3e2aaaab
	v_fma_f32 v1, v2, v1, 0.5
	v_fma_f32 v1, v2, v1, 1.0
	v_mul_f32_e32 v1, v2, v1
	v_cmp_gt_f32_e32 vcc, s95, v2
	s_and_saveexec_b64 s[0:1], vcc
	s_cbranch_execz .LBB0_284
	v_mul_f32_e32 v1, 0x3fb8aa3b, v2
	v_rndne_f32_e32 v1, v1
	v_fmamk_f32 v3, v1, 0xbf317218, v2
	v_fmac_f32_e32 v3, 0x3102e308, v1
	v_fmamk_f32 v4, v3, 0x395133b1, v159
	v_cmp_eq_f32_e32 vcc, s96, v1
	v_cvt_i32_f32_e32 v1, v1
	v_fmaak_f32 v4, v3, v4, 0x3c0887f9
	v_fmaak_f32 v4, v3, v4, 0x3d2aaa81
	v_fmaak_f32 v4, v3, v4, 0x3e2aaaab
	v_fma_f32 v4, v3, v4, 0.5
	v_ldexp_f32 v1, 1.0, v1
	v_mul_f32_e32 v4, v3, v4
	v_cndmask_b32_e32 v1, v1, v171, vcc
	v_fmac_f32_e32 v3, v3, v4
	v_add_f32_e32 v4, -1.0, v1
	v_fmac_f32_e32 v4, v1, v3
	v_add_f32_e32 v1, v4, v4
	v_cndmask_b32_e32 v1, v4, v1, vcc
	v_cmp_ngt_f32_e32 vcc, s97, v2
	s_nop 1
	v_cndmask_b32_e32 v1, -1.0, v1, vcc
.LBB0_284:
	s_or_b64 exec, exec, s[0:1]
	v_add_f32_e32 v2, v86, v13
	v_mul_f32_e32 v2, 0xbfb8aa3b, v2
	v_exp_f32_e32 v2, v2
	v_lshl_add_u32 v97, v0, 2, v173
	v_add_f32_e32 v2, 1.0, v2
	s_nop 0
	v_add_f32_e32 v4, 2.0, v1
	v_rcp_f32_e32 v2, v2
	s_nop 0
	v_add_f32_e32 v3, 1.0, v1
	v_mul_f32_e64 v1, v4, -v1
	v_cmp_gt_f32_e32 vcc, s28, v1
	v_mul_f32_e32 v4, 0x4f800000, v1
	ds_write_b32 v81, v3 offset:50432
	v_cndmask_b32_e32 v1, v1, v4, vcc
	v_sqrt_f32_e32 v4, v1
	s_nop 0
	v_add_u32_e32 v5, -1, v4
	v_fma_f32 v6, -v5, v4, v1
	v_cmp_ge_f32_e64 s[0:1], 0, v6
	v_add_u32_e32 v6, 1, v4
	s_nop 0
	v_cndmask_b32_e64 v5, v4, v5, s[0:1]
	v_fma_f32 v4, -v6, v4, v1
	v_cmp_lt_f32_e64 s[0:1], 0, v4
	s_nop 1
	v_cndmask_b32_e64 v4, v5, v6, s[0:1]
	v_mul_f32_e32 v5, 0x37800000, v4
	v_cndmask_b32_e32 v4, v4, v5, vcc
	v_cmp_class_f32_e32 vcc, v1, v160
	s_nop 1
	v_cndmask_b32_e32 v1, v4, v1, vcc
	ds_read_b32 v4, v81 offset:15616
	s_waitcnt lgkmcnt(0)
	v_mul_f32_e32 v2, v2, v4
	v_mul_f32_e32 v1, v2, v1
	ds_write_b32 v97, v1
	v_add_f32_e32 v1, v88, v30
	v_mul_f32_e32 v1, 0xbfb8aa3b, v1
	v_exp_f32_e32 v1, v1
	s_nop 0
	v_add_f32_e32 v1, 1.0, v1
	s_nop 0
	v_rcp_f32_e32 v1, v1
	s_nop 0
	v_mul_f32_e32 v1, 0xc1000000, v1
	v_mul_f32_e32 v2, v1, v16
	v_fmamk_f32 v1, v2, 0x3ab60b61, v158
	v_fmaak_f32 v1, v2, v1, 0x3d2aaaab
	v_fmaak_f32 v1, v2, v1, 0x3e2aaaab
	v_fma_f32 v1, v2, v1, 0.5
	v_fma_f32 v1, v2, v1, 1.0
	v_mul_f32_e32 v1, v2, v1
	v_cmp_gt_f32_e32 vcc, s95, v2
	s_and_saveexec_b64 s[0:1], vcc
	s_cbranch_execz .LBB0_286
	v_mul_f32_e32 v1, 0x3fb8aa3b, v2
	v_rndne_f32_e32 v1, v1
	v_fmamk_f32 v3, v1, 0xbf317218, v2
	v_fmac_f32_e32 v3, 0x3102e308, v1
	v_fmamk_f32 v4, v3, 0x395133b1, v159
	v_cmp_eq_f32_e32 vcc, s96, v1
	v_cvt_i32_f32_e32 v1, v1
	v_fmaak_f32 v4, v3, v4, 0x3c0887f9
	v_fmaak_f32 v4, v3, v4, 0x3d2aaa81
	v_fmaak_f32 v4, v3, v4, 0x3e2aaaab
	v_fma_f32 v4, v3, v4, 0.5
	v_ldexp_f32 v1, 1.0, v1
	v_mul_f32_e32 v4, v3, v4
	v_cndmask_b32_e32 v1, v1, v171, vcc
	v_fmac_f32_e32 v3, v3, v4
	v_add_f32_e32 v4, -1.0, v1
	v_fmac_f32_e32 v4, v1, v3
	v_add_f32_e32 v1, v4, v4
	v_cndmask_b32_e32 v1, v4, v1, vcc
	v_cmp_ngt_f32_e32 vcc, s97, v2
	s_nop 1
	v_cndmask_b32_e32 v1, -1.0, v1, vcc
.LBB0_286:
	s_or_b64 exec, exec, s[0:1]
	v_add_f32_e32 v2, v86, v14
	v_mul_f32_e32 v2, 0xbfb8aa3b, v2
	v_exp_f32_e32 v2, v2
	v_lshl_add_u32 v98, v0, 2, v174
	v_add_f32_e32 v2, 1.0, v2
	s_nop 0
	v_add_f32_e32 v4, 2.0, v1
	v_rcp_f32_e32 v2, v2
	s_nop 0
	v_add_f32_e32 v3, 1.0, v1
	v_mul_f32_e64 v1, v4, -v1
	v_cmp_gt_f32_e32 vcc, s28, v1
	v_mul_f32_e32 v4, 0x4f800000, v1
	ds_write_b32 v81, v3 offset:50688
	v_cndmask_b32_e32 v1, v1, v4, vcc
	v_sqrt_f32_e32 v4, v1
	s_nop 0
	v_add_u32_e32 v5, -1, v4
	v_fma_f32 v6, -v5, v4, v1
	v_cmp_ge_f32_e64 s[0:1], 0, v6
	v_add_u32_e32 v6, 1, v4
	s_nop 0
	v_cndmask_b32_e64 v5, v4, v5, s[0:1]
	v_fma_f32 v4, -v6, v4, v1
	v_cmp_lt_f32_e64 s[0:1], 0, v4
	s_nop 1
	v_cndmask_b32_e64 v4, v5, v6, s[0:1]
	v_mul_f32_e32 v5, 0x37800000, v4
	v_cndmask_b32_e32 v4, v4, v5, vcc
	v_cmp_class_f32_e32 vcc, v1, v160
	s_nop 1
	v_cndmask_b32_e32 v1, v4, v1, vcc
	ds_read_b32 v4, v81 offset:15872
	s_waitcnt lgkmcnt(0)
	v_mul_f32_e32 v2, v2, v4
	v_mul_f32_e32 v1, v2, v1
	ds_write_b32 v98, v1
	v_add_f32_e32 v1, v88, v31
	v_mul_f32_e32 v1, 0xbfb8aa3b, v1
	v_exp_f32_e32 v1, v1
	s_nop 0
	v_add_f32_e32 v1, 1.0, v1
	s_nop 0
	v_rcp_f32_e32 v1, v1
	s_nop 0
	v_mul_f32_e32 v1, 0xc1000000, v1
	v_mul_f32_e32 v1, v1, v16
	v_fmamk_f32 v2, v1, 0x3ab60b61, v158
	v_fmaak_f32 v2, v1, v2, 0x3d2aaaab
	v_fmaak_f32 v2, v1, v2, 0x3e2aaaab
	v_fma_f32 v2, v1, v2, 0.5
	v_fma_f32 v2, v1, v2, 1.0
	v_mul_f32_e32 v2, v1, v2
	v_cmp_gt_f32_e32 vcc, s95, v1
	s_and_saveexec_b64 s[0:1], vcc
	s_cbranch_execz .LBB0_288
	v_mul_f32_e32 v2, 0x3fb8aa3b, v1
	v_rndne_f32_e32 v2, v2
	v_fmamk_f32 v3, v2, 0xbf317218, v1
	v_fmac_f32_e32 v3, 0x3102e308, v2
	v_fmamk_f32 v4, v3, 0x395133b1, v159
	v_cmp_eq_f32_e32 vcc, s96, v2
	v_cvt_i32_f32_e32 v2, v2
	v_fmaak_f32 v4, v3, v4, 0x3c0887f9
	v_fmaak_f32 v4, v3, v4, 0x3d2aaa81
	v_fmaak_f32 v4, v3, v4, 0x3e2aaaab
	v_fma_f32 v4, v3, v4, 0.5
	v_ldexp_f32 v2, 1.0, v2
	v_mul_f32_e32 v4, v3, v4
	v_cndmask_b32_e32 v2, v2, v171, vcc
	v_fmac_f32_e32 v3, v3, v4
	v_add_f32_e32 v4, -1.0, v2
	v_fmac_f32_e32 v4, v2, v3
	v_add_f32_e32 v2, v4, v4
	v_cndmask_b32_e32 v2, v4, v2, vcc
	v_cmp_ngt_f32_e32 vcc, s97, v1
	s_nop 1
	v_cndmask_b32_e32 v2, -1.0, v2, vcc
.LBB0_288:
	s_or_b64 exec, exec, s[0:1]
	v_add_f32_e32 v1, v86, v15
	v_mul_f32_e32 v1, 0xbfb8aa3b, v1
	v_exp_f32_e32 v1, v1
	v_add_f32_e32 v3, 2.0, v2
	v_mul_f32_e64 v3, v3, -v2
	v_mul_f32_e32 v6, 0x4f800000, v3
	v_add_f32_e32 v1, 1.0, v1
	v_cmp_gt_f32_e64 s[0:1], s28, v3
	v_cndmask_b32_e64 v3, v3, v6, s[0:1]
	v_sqrt_f32_e32 v6, v3
	v_rcp_f32_e32 v1, v1
	s_nop 0
	v_add_u32_e32 v4, -1, v6
	v_fma_f32 v5, -v4, v6, v3
	v_cmp_ge_f32_e32 vcc, 0, v5
	v_add_u32_e32 v5, 1, v6
	v_add_f32_e32 v2, 1.0, v2
	v_cndmask_b32_e32 v4, v6, v4, vcc
	v_fma_f32 v6, -v5, v6, v3
	v_cmp_lt_f32_e32 vcc, 0, v6
	v_lshl_add_u32 v96, v0, 2, v175
	ds_write_b32 v81, v2 offset:50944
	v_cndmask_b32_e32 v4, v4, v5, vcc
	ds_read_b32 v5, v81 offset:16128
	v_mul_f32_e32 v6, 0x37800000, v4
	v_cndmask_b32_e64 v4, v4, v6, s[0:1]
	v_cmp_class_f32_e32 vcc, v3, v160
	v_lshlrev_b32_e32 v7, 2, v51
	s_waitcnt lgkmcnt(0)
	v_mul_f32_e32 v1, v1, v5
	v_cndmask_b32_e32 v3, v4, v3, vcc
	v_mul_f32_e32 v1, v1, v3
	ds_write_b32 v96, v1
	s_waitcnt lgkmcnt(0)
	s_barrier
	ds_read2st64_b32 v[0:1], v105 offset0:172 offset1:236
	v_cmp_lt_i32_e64 s[42:43], 0, v49
	v_or_b32_e32 v88, 0x13000, v83
	v_add_u32_e32 v86, 0x12c00, v7
	v_add_u32_e32 v92, 0x13000, v7
	s_waitcnt lgkmcnt(0)
	v_fma_f32 v1, 0, v0, v1
	ds_write_b32 v105, v1 offset:60416
	ds_read2st64_b32 v[2:3], v104 offset0:172 offset1:236
	v_or_b32_e32 v89, 0x12c00, v83
	s_waitcnt lgkmcnt(0)
	v_mul_f32_e32 v4, v0, v2
	v_fmac_f32_e32 v3, v1, v2
	ds_write2st64_b32 v104, v4, v3 offset0:172 offset1:236
	ds_read2st64_b32 v[0:1], v53 offset0:172 offset1:236
	s_waitcnt lgkmcnt(0)
	v_mul_f32_e32 v4, v4, v0
	v_fmac_f32_e32 v1, v3, v0
	ds_write2st64_b32 v53, v4, v1 offset0:172 offset1:236
	ds_read2st64_b32 v[2:3], v55 offset0:172 offset1:236
	s_waitcnt lgkmcnt(0)
	v_mul_f32_e32 v4, v4, v2
	v_fmac_f32_e32 v3, v1, v2
	ds_write2st64_b32 v55, v4, v3 offset0:172 offset1:236
	ds_read2st64_b32 v[0:1], v57 offset0:172 offset1:236
	s_waitcnt lgkmcnt(0)
	v_mul_f32_e32 v4, v4, v0
	v_fmac_f32_e32 v1, v3, v0
	ds_write2st64_b32 v57, v4, v1 offset0:172 offset1:236
	ds_read2st64_b32 v[2:3], v59 offset0:172 offset1:236
	s_waitcnt lgkmcnt(0)
	v_mul_f32_e32 v4, v4, v2
	v_fmac_f32_e32 v3, v1, v2
	ds_write2st64_b32 v59, v4, v3 offset0:172 offset1:236
	ds_read2st64_b32 v[0:1], v61 offset0:172 offset1:236
	s_waitcnt lgkmcnt(0)
	v_mul_f32_e32 v4, v4, v0
	v_fmac_f32_e32 v1, v3, v0
	ds_write2st64_b32 v61, v4, v1 offset0:172 offset1:236
	ds_read2st64_b32 v[2:3], v63 offset0:172 offset1:236
	s_waitcnt lgkmcnt(0)
	v_mul_f32_e32 v4, v4, v2
	v_fmac_f32_e32 v3, v1, v2
	ds_write2st64_b32 v63, v4, v3 offset0:172 offset1:236
	ds_read2st64_b32 v[0:1], v65 offset0:172 offset1:236
	s_waitcnt lgkmcnt(0)
	v_mul_f32_e32 v4, v4, v0
	v_fmac_f32_e32 v1, v3, v0
	ds_write2st64_b32 v65, v4, v1 offset0:172 offset1:236
	ds_read2st64_b32 v[2:3], v67 offset0:172 offset1:236
	s_waitcnt lgkmcnt(0)
	v_mul_f32_e32 v4, v4, v2
	v_fmac_f32_e32 v3, v1, v2
	ds_write2st64_b32 v67, v4, v3 offset0:172 offset1:236
	ds_read2st64_b32 v[0:1], v69 offset0:172 offset1:236
	s_waitcnt lgkmcnt(0)
	v_mul_f32_e32 v4, v4, v0
	v_fmac_f32_e32 v1, v3, v0
	ds_write2st64_b32 v69, v4, v1 offset0:172 offset1:236
	ds_read2st64_b32 v[2:3], v71 offset0:172 offset1:236
	s_waitcnt lgkmcnt(0)
	v_mul_f32_e32 v4, v4, v2
	v_fmac_f32_e32 v3, v1, v2
	ds_write2st64_b32 v71, v4, v3 offset0:172 offset1:236
	ds_read2st64_b32 v[0:1], v73 offset0:172 offset1:236
	s_waitcnt lgkmcnt(0)
	v_mul_f32_e32 v4, v4, v0
	v_fmac_f32_e32 v1, v3, v0
	ds_write2st64_b32 v73, v4, v1 offset0:172 offset1:236
	ds_read2st64_b32 v[2:3], v75 offset0:172 offset1:236
	v_mov_b32_e32 v0, 1.0
	s_waitcnt lgkmcnt(0)
	v_mul_f32_e32 v6, v4, v2
	v_fmac_f32_e32 v3, v1, v2
	ds_write2st64_b32 v75, v6, v3 offset0:172 offset1:236
	ds_read2st64_b32 v[4:5], v77 offset0:172 offset1:236
	v_mov_b32_e32 v1, 0
	s_waitcnt lgkmcnt(0)
	v_mul_f32_e32 v6, v6, v4
	v_fmac_f32_e32 v5, v3, v4
	ds_write2st64_b32 v77, v6, v5 offset0:172 offset1:236
	ds_read2st64_b32 v[2:3], v79 offset0:172 offset1:236
	s_waitcnt lgkmcnt(0)
	v_mul_f32_e32 v4, v6, v2
	v_fmac_f32_e32 v3, v5, v2
	ds_write2st64_b32 v79, v4, v3 offset0:172 offset1:236
	ds_write_b32 v86, v4
	ds_write_b32 v92, v3
	s_waitcnt lgkmcnt(0)
	s_barrier
	s_and_saveexec_b64 s[0:1], s[42:43]
	s_cbranch_execz .LBB0_290
	ds_read_b32 v0, v89
	ds_read_b32 v1, v88
	s_waitcnt lgkmcnt(0)
	v_fmac_f32_e32 v1, 0, v0

.LBB0_296:
	s_or_b64 exec, exec, s[0:1]
	s_barrier
	ds_write_b128 v100, v[32:35] offset:25600
	ds_write_b128 v101, v[36:39] offset:25600
	ds_write_b128 v102, v[40:43] offset:25600
	ds_write_b128 v103, v[44:47] offset:25600
	s_waitcnt lgkmcnt(0)
	s_barrier
	ds_read_b128 v[0:3], v99 offset:34816
	ds_read_b128 v[4:7], v80
	ds_read_b128 v[32:35], v80 offset:32
	ds_read_b128 v[8:11], v99 offset:25600
	ds_read_b128 v[36:39], v99 offset:25632
	s_waitcnt lgkmcnt(1)
	v_mfma_f32_32x32x16_bf16 v[16:31], v[4:7], v[8:11], 0
	ds_read_b128 v[40:43], v99 offset:34848
	s_mov_b32 s0, 0xbfb8aa3b
	v_mfma_f32_32x32x16_bf16 v[0:15], v[4:7], v[0:3], 0
	s_waitcnt lgkmcnt(1)
	v_mfma_f32_32x32x16_bf16 v[16:31], v[32:35], v[36:39], v[16:31]
	s_waitcnt lgkmcnt(0)
	v_mfma_f32_32x32x16_bf16 v[0:15], v[32:35], v[40:43], v[0:15]
	ds_read_b128 v[32:35], v80 offset:64
	ds_read_b128 v[36:39], v99 offset:25664
	ds_read_b128 v[40:43], v99 offset:34880
	s_waitcnt lgkmcnt(1)
	v_mfma_f32_32x32x16_bf16 v[16:31], v[32:35], v[36:39], v[16:31]
	s_waitcnt lgkmcnt(0)
	v_mfma_f32_32x32x16_bf16 v[0:15], v[32:35], v[40:43], v[0:15]
	ds_read_b128 v[32:35], v80 offset:96
	ds_read_b128 v[36:39], v99 offset:25696
	ds_read_b128 v[40:43], v99 offset:34912
	s_waitcnt lgkmcnt(1)
	v_mfma_f32_32x32x16_bf16 v[16:31], v[32:35], v[36:39], v[16:31]
	s_waitcnt lgkmcnt(0)
	v_mfma_f32_32x32x16_bf16 v[0:15], v[32:35], v[40:43], v[0:15]
	s_waitcnt vmcnt(33)
	v_mul_f32_e32 v32, 0xbfb8aa3b, v87
	v_rndne_f32_e32 v33, v32
	v_sub_f32_e32 v34, v32, v33
	v_fma_f32 v32, v87, s0, -v32
	v_fmac_f32_e32 v32, 0xb2a5705f, v87
	v_add_f32_e32 v32, v34, v32
	v_exp_f32_e32 v32, v32
	v_cvt_i32_f32_e32 v33, v33
	s_mov_b32 s0, 0x42ce8ed0
	v_cmp_nlt_f32_e32 vcc, s0, v87
	s_mov_b32 s0, 0xc2b17218
	v_ldexp_f32 v32, v32, v33
	v_cndmask_b32_e32 v32, 0, v32, vcc
	v_cmp_ngt_f32_e32 vcc, s0, v87
	s_mov_b32 s0, 0x3f2aaaab
	s_waitcnt vmcnt(32)
	v_add_f32_e32 v16, v85, v16
	v_cndmask_b32_e32 v46, v170, v32, vcc
	v_add_f32_e32 v34, 1.0, v46
	v_add_f32_e32 v32, -1.0, v34
	v_sub_f32_e32 v33, v32, v34
	v_add_f32_e32 v33, 1.0, v33
	v_sub_f32_e32 v32, v46, v32
	v_add_f32_e32 v35, v32, v33
	v_frexp_mant_f32_e32 v32, v34
	v_cmp_gt_f32_e32 vcc, s0, v32
	v_cvt_f64_f32_e32 v[32:33], v34
	v_frexp_exp_i32_f64_e32 v32, v[32:33]
	v_subbrev_co_u32_e32 v40, vcc, 0, v32, vcc
	v_sub_u32_e32 v32, 0, v40
	v_ldexp_f32 v33, v34, v32
	v_add_f32_e32 v34, -1.0, v33
	v_add_f32_e32 v36, 1.0, v33
	v_ldexp_f32 v32, v35, v32
	v_add_f32_e32 v35, 1.0, v34
	v_add_f32_e32 v37, -1.0, v36
	v_sub_f32_e32 v35, v33, v35
	v_sub_f32_e32 v33, v33, v37
	v_add_f32_e32 v35, v32, v35
	v_add_f32_e32 v32, v32, v33
	v_add_f32_e32 v41, v36, v32
	v_rcp_f32_e32 v43, v41
	v_sub_f32_e32 v33, v36, v41
	v_add_f32_e32 v42, v32, v33
	v_add_f32_e32 v33, v34, v35
	v_mul_f32_e32 v45, v33, v43
	v_sub_f32_e32 v32, v34, v33
	v_mul_f32_e32 v34, v41, v45
	v_fma_f32 v36, v45, v41, -v34
	v_fmac_f32_e32 v36, v45, v42
	v_add_f32_e32 v44, v35, v32
	v_add_f32_e32 v32, v34, v36
	v_sub_f32_e32 v35, v33, v32
	v_pk_add_f32 v[38:39], v[32:33], v[34:35] neg_lo:[0,1] neg_hi:[0,1]
	v_mov_b32_e32 v37, v32
	v_pk_add_f32 v[32:33], v[38:39], v[36:37] neg_lo:[0,1] neg_hi:[0,1]
	s_mov_b32 s0, 0x3f317218
	v_add_f32_e32 v33, v44, v33
	v_add_f32_e32 v32, v32, v33
	v_add_f32_e32 v33, v35, v32
	v_mul_f32_e32 v44, v43, v33
	v_mul_f32_e32 v34, v41, v44
	v_fma_f32 v36, v44, v41, -v34
	v_fmac_f32_e32 v36, v44, v42
	v_sub_f32_e32 v35, v35, v33
	v_add_f32_e32 v41, v32, v35
	v_add_f32_e32 v32, v34, v36
	v_sub_f32_e32 v35, v33, v32
	v_pk_add_f32 v[38:39], v[32:33], v[34:35] neg_lo:[0,1] neg_hi:[0,1]
	v_mov_b32_e32 v37, v32
	v_pk_add_f32 v[32:33], v[38:39], v[36:37] neg_lo:[0,1] neg_hi:[0,1]
	v_mul_f32_e32 v16, 0xbfb8aa3b, v16
	v_add_f32_e32 v33, v41, v33
	v_add_f32_e32 v32, v32, v33
	v_add_f32_e32 v33, v45, v44
	v_add_f32_e32 v32, v35, v32
	v_sub_f32_e32 v34, v33, v45
	v_mul_f32_e32 v32, v43, v32
	v_sub_f32_e32 v34, v44, v34
	v_add_f32_e32 v34, v34, v32
	v_add_f32_e32 v36, v33, v34
	v_mul_f32_e32 v37, v36, v36
	v_fmamk_f32 v32, v37, 0x3e9b6dac, v157
	v_fmaak_f32 v129, v37, v32, 0x3f2aaada
	v_cvt_f32_i32_e32 v32, v40
	v_sub_f32_e32 v33, v36, v33
	v_sub_f32_e32 v33, v34, v33
	v_ldexp_f32 v38, v33, 1
	v_mul_f32_e32 v33, v36, v37
	v_ldexp_f32 v35, v36, 1
	v_pk_mul_f32 v[36:37], v[32:33], v[128:129]
	v_exp_f32_e32 v16, v16
	v_fma_f32 v34, v32, s0, -v36
	v_fmac_f32_e32 v34, 0xb102e308, v32
	v_pk_add_f32 v[32:33], v[36:37], v[34:35]
	v_cmp_neq_f32_e32 vcc, s94, v46
	v_sub_f32_e32 v35, v33, v35
	v_sub_f32_e32 v35, v37, v35
	v_add_f32_e32 v39, v38, v35
	v_mov_b32_e32 v38, v36
	v_pk_add_f32 v[36:37], v[32:33], v[36:37] neg_lo:[0,1] neg_hi:[0,1]
	v_pk_add_f32 v[40:41], v[32:33], v[38:39]
	v_mov_b32_e32 v35, v32
	v_mov_b32_e32 v37, v41
	v_pk_add_f32 v[42:43], v[34:35], v[36:37] neg_lo:[0,1] neg_hi:[0,1]
	v_pk_add_f32 v[34:35], v[34:35], v[36:37]
	v_mov_b32_e32 v38, v39
	v_pk_add_f32 v[36:37], v[34:35], v[32:33] op_sel:[1,0] op_sel_hi:[0,1] neg_lo:[0,1] neg_hi:[0,1]
	v_pk_add_f32 v[44:45], v[40:41], v[36:37] op_sel_hi:[1,0] neg_lo:[0,1] neg_hi:[0,1]
	v_mov_b32_e32 v40, v41
	v_mov_b32_e32 v41, v35
	v_pk_mov_b32 v[36:37], v[32:33], v[36:37] op_sel:[1,0]
	v_mov_b32_e32 v39, v32
	v_pk_add_f32 v[36:37], v[40:41], v[36:37] neg_lo:[0,1] neg_hi:[0,1]
	v_mov_b32_e32 v44, v42
	v_pk_add_f32 v[32:33], v[38:39], v[36:37] neg_lo:[0,1] neg_hi:[0,1]
	v_mov_b32_e32 v43, v35
	v_pk_add_f32 v[36:37], v[44:45], v[32:33]
	s_mov_b32 s0, 0x33800000
	v_pk_add_f32 v[38:39], v[36:37], v[36:37] op_sel:[0,1] op_sel_hi:[1,0]
	v_add_f32_e32 v16, 1.0, v16
	v_pk_add_f32 v[34:35], v[34:35], v[38:39] op_sel:[1,0] op_sel_hi:[0,1]
	v_mov_b32_e32 v37, v34
	v_pk_add_f32 v[40:41], v[36:37], v[42:43] neg_lo:[0,1] neg_hi:[0,1]
	v_mov_b32_e32 v33, v38
	v_sub_f32_e32 v35, v36, v40
	v_pk_add_f32 v[32:33], v[32:33], v[40:41] neg_lo:[0,1] neg_hi:[0,1]
	v_sub_f32_e32 v35, v42, v35
	v_add_f32_e32 v32, v32, v35
	v_add_f32_e32 v32, v32, v33
	v_add_f32_e32 v32, v34, v32
	v_cndmask_b32_e32 v32, v170, v32, vcc
	v_cmp_lt_f32_e64 vcc, |v46|, s0
	v_cndmask_b32_e32 v32, v32, v46, vcc
	v_rcp_f32_e64 v16, -v16
	s_nop 0
	v_mul_f32_e32 v16, 0x41000000, v16
	v_mul_f32_e32 v33, v16, v32
	v_fmamk_f32 v16, v33, 0x3ab60b61, v158
	v_fmaak_f32 v16, v33, v16, 0x3d2aaaab
	v_fmaak_f32 v16, v33, v16, 0x3e2aaaab
	v_fma_f32 v16, v33, v16, 0.5
	v_fma_f32 v16, v33, v16, 1.0
	v_mul_f32_e32 v16, v33, v16
	v_cmp_gt_f32_e32 vcc, s95, v33
	s_and_saveexec_b64 s[0:1], vcc
	s_cbranch_execz .LBB0_298
	v_mul_f32_e32 v16, 0x3fb8aa3b, v33
	v_rndne_f32_e32 v16, v16
	v_fmamk_f32 v34, v16, 0xbf317218, v33
	v_fmac_f32_e32 v34, 0x3102e308, v16
	v_fmamk_f32 v35, v34, 0x395133b1, v159
	v_cmp_eq_f32_e32 vcc, s96, v16
	v_cvt_i32_f32_e32 v16, v16
	v_fmaak_f32 v35, v34, v35, 0x3c0887f9
	v_fmaak_f32 v35, v34, v35, 0x3d2aaa81
	v_fmaak_f32 v35, v34, v35, 0x3e2aaaab
	v_fma_f32 v35, v34, v35, 0.5
	v_ldexp_f32 v16, 1.0, v16
	v_mul_f32_e32 v35, v34, v35
	v_cndmask_b32_e32 v16, v16, v171, vcc
	v_fmac_f32_e32 v34, v34, v35
	v_add_f32_e32 v35, -1.0, v16
	v_fmac_f32_e32 v35, v16, v34
	v_add_f32_e32 v16, v35, v35
	v_cndmask_b32_e32 v16, v35, v16, vcc
	v_cmp_ngt_f32_e32 vcc, s97, v33
	s_nop 1
	v_cndmask_b32_e32 v16, -1.0, v16, vcc
.LBB0_298:
	s_or_b64 exec, exec, s[0:1]
	v_add_f32_e32 v0, v84, v0
	v_mul_f32_e32 v0, 0xbfb8aa3b, v0
	v_exp_f32_e32 v0, v0
	s_nop 0
	v_add_f32_e32 v0, 1.0, v0
	s_nop 0
	v_add_f32_e32 v34, 2.0, v16
	v_rcp_f32_e32 v0, v0
	s_nop 0
	v_add_f32_e32 v33, 1.0, v16
	v_mul_f32_e64 v16, v34, -v16
	v_cmp_gt_f32_e32 vcc, s28, v16
	v_mul_f32_e32 v34, 0x4f800000, v16
	s_nop 0
	v_cndmask_b32_e32 v16, v16, v34, vcc
	v_sqrt_f32_e32 v34, v16
	s_nop 0
	v_add_u32_e32 v35, -1, v34
	v_fma_f32 v36, -v35, v34, v16
	v_cmp_ge_f32_e64 s[0:1], 0, v36
	v_add_u32_e32 v36, 1, v34
	s_nop 0
	v_cndmask_b32_e64 v35, v34, v35, s[0:1]
	v_fma_f32 v34, -v36, v34, v16
	v_cmp_lt_f32_e64 s[0:1], 0, v34
	s_nop 1
	v_cndmask_b32_e64 v34, v35, v36, s[0:1]
	v_mul_f32_e32 v35, 0x37800000, v34
	v_cndmask_b32_e32 v34, v34, v35, vcc
	v_cmp_class_f32_e32 vcc, v16, v160
	s_nop 1
	v_cndmask_b32_e32 v16, v34, v16, vcc
	ds_read_b32 v34, v81 offset:9216
	s_waitcnt lgkmcnt(0)
	v_mul_f32_e32 v0, v0, v34
	v_mul_f32_e32 v0, v0, v16
	ds_write2st64_b32 v81, v33, v0 offset0:172 offset1:236
	v_add_f32_e32 v0, v85, v17
	v_mul_f32_e32 v0, 0xbfb8aa3b, v0
	v_exp_f32_e32 v0, v0
	s_nop 0
	v_add_f32_e32 v0, 1.0, v0
	s_nop 0
	v_rcp_f32_e32 v0, v0
	s_nop 0
	v_mul_f32_e32 v0, 0xc1000000, v0
	v_mul_f32_e32 v16, v0, v32
	v_fmamk_f32 v0, v16, 0x3ab60b61, v158
	v_fmaak_f32 v0, v16, v0, 0x3d2aaaab
	v_fmaak_f32 v0, v16, v0, 0x3e2aaaab
	v_fma_f32 v0, v16, v0, 0.5
	v_fma_f32 v0, v16, v0, 1.0
	v_mul_f32_e32 v0, v16, v0
	v_cmp_gt_f32_e32 vcc, s95, v16
	s_and_saveexec_b64 s[0:1], vcc
	s_cbranch_execz .LBB0_300
	v_mul_f32_e32 v0, 0x3fb8aa3b, v16
	v_rndne_f32_e32 v0, v0
	v_fmamk_f32 v17, v0, 0xbf317218, v16
	v_fmac_f32_e32 v17, 0x3102e308, v0
	v_fmamk_f32 v33, v17, 0x395133b1, v159
	v_cmp_eq_f32_e32 vcc, s96, v0
	v_cvt_i32_f32_e32 v0, v0
	v_fmaak_f32 v33, v17, v33, 0x3c0887f9
	v_fmaak_f32 v33, v17, v33, 0x3d2aaa81
	v_fmaak_f32 v33, v17, v33, 0x3e2aaaab
	v_fma_f32 v33, v17, v33, 0.5
	v_ldexp_f32 v0, 1.0, v0
	v_mul_f32_e32 v33, v17, v33
	v_cndmask_b32_e32 v0, v0, v171, vcc
	v_fmac_f32_e32 v17, v17, v33
	v_add_f32_e32 v33, -1.0, v0
	v_fmac_f32_e32 v33, v0, v17
	v_add_f32_e32 v0, v33, v33
	v_cndmask_b32_e32 v0, v33, v0, vcc
	v_cmp_ngt_f32_e32 vcc, s97, v16
	s_nop 1
	v_cndmask_b32_e32 v0, -1.0, v0, vcc
.LBB0_300:
	s_or_b64 exec, exec, s[0:1]
	v_add_f32_e32 v1, v84, v1
	v_mul_f32_e32 v1, 0xbfb8aa3b, v1
	v_exp_f32_e32 v1, v1
	s_nop 0
	v_add_f32_e32 v1, 1.0, v1
	s_nop 0
	v_add_f32_e32 v17, 2.0, v0
	v_rcp_f32_e32 v1, v1
	s_nop 0
	v_add_f32_e32 v16, 1.0, v0
	v_mul_f32_e64 v0, v17, -v0
	v_cmp_gt_f32_e32 vcc, s28, v0
	v_mul_f32_e32 v17, 0x4f800000, v0
	s_nop 0
	v_cndmask_b32_e32 v0, v0, v17, vcc
	v_sqrt_f32_e32 v17, v0
	s_nop 0
	v_add_u32_e32 v33, -1, v17
	v_fma_f32 v34, -v33, v17, v0
	v_cmp_ge_f32_e64 s[0:1], 0, v34
	v_add_u32_e32 v34, 1, v17
	s_nop 0
	v_cndmask_b32_e64 v33, v17, v33, s[0:1]
	v_fma_f32 v17, -v34, v17, v0
	v_cmp_lt_f32_e64 s[0:1], 0, v17
	s_nop 1
	v_cndmask_b32_e64 v17, v33, v34, s[0:1]
	v_mul_f32_e32 v33, 0x37800000, v17
	v_cndmask_b32_e32 v17, v17, v33, vcc
	v_cmp_class_f32_e32 vcc, v0, v160
	s_nop 1
	v_cndmask_b32_e32 v0, v17, v0, vcc
	ds_read_b32 v17, v81 offset:9472
	s_waitcnt lgkmcnt(0)
	v_mul_f32_e32 v1, v1, v17
	v_mul_f32_e32 v0, v1, v0
	ds_write2st64_b32 v81, v16, v0 offset0:173 offset1:237
	v_add_f32_e32 v0, v85, v18
	v_mul_f32_e32 v0, 0xbfb8aa3b, v0
	v_exp_f32_e32 v0, v0
	s_nop 0
	v_add_f32_e32 v0, 1.0, v0
	s_nop 0
	v_rcp_f32_e32 v0, v0
	s_nop 0
	v_mul_f32_e32 v0, 0xc1000000, v0
	v_mul_f32_e32 v1, v0, v32
	v_fmamk_f32 v0, v1, 0x3ab60b61, v158
	v_fmaak_f32 v0, v1, v0, 0x3d2aaaab
	v_fmaak_f32 v0, v1, v0, 0x3e2aaaab
	v_fma_f32 v0, v1, v0, 0.5
	v_fma_f32 v0, v1, v0, 1.0
	v_mul_f32_e32 v0, v1, v0
	v_cmp_gt_f32_e32 vcc, s95, v1
	s_and_saveexec_b64 s[0:1], vcc
	s_cbranch_execz .LBB0_302
	v_mul_f32_e32 v0, 0x3fb8aa3b, v1
	v_rndne_f32_e32 v0, v0
	v_fmamk_f32 v16, v0, 0xbf317218, v1
	v_fmac_f32_e32 v16, 0x3102e308, v0
	v_fmamk_f32 v17, v16, 0x395133b1, v159
	v_cmp_eq_f32_e32 vcc, s96, v0
	v_cvt_i32_f32_e32 v0, v0
	v_fmaak_f32 v17, v16, v17, 0x3c0887f9
	v_fmaak_f32 v17, v16, v17, 0x3d2aaa81
	v_fmaak_f32 v17, v16, v17, 0x3e2aaaab
	v_fma_f32 v17, v16, v17, 0.5
	v_ldexp_f32 v0, 1.0, v0
	v_mul_f32_e32 v17, v16, v17
	v_cndmask_b32_e32 v0, v0, v171, vcc
	v_fmac_f32_e32 v16, v16, v17
	v_add_f32_e32 v17, -1.0, v0
	v_fmac_f32_e32 v17, v0, v16
	v_add_f32_e32 v0, v17, v17
	v_cndmask_b32_e32 v0, v17, v0, vcc
	v_cmp_ngt_f32_e32 vcc, s97, v1
	s_nop 1
	v_cndmask_b32_e32 v0, -1.0, v0, vcc
.LBB0_302:
	s_or_b64 exec, exec, s[0:1]
	v_add_f32_e32 v1, v84, v2
	v_mul_f32_e32 v1, 0xbfb8aa3b, v1
	v_exp_f32_e32 v1, v1
	s_nop 0
	v_add_f32_e32 v1, 1.0, v1
	s_nop 0
	v_add_f32_e32 v16, 2.0, v0
	v_rcp_f32_e32 v1, v1
	s_nop 0
	v_add_f32_e32 v2, 1.0, v0
	v_mul_f32_e64 v0, v16, -v0
	v_cmp_gt_f32_e32 vcc, s28, v0
	v_mul_f32_e32 v16, 0x4f800000, v0
	s_nop 0
	v_cndmask_b32_e32 v0, v0, v16, vcc
	v_sqrt_f32_e32 v16, v0
	s_nop 0
	v_add_u32_e32 v17, -1, v16
	v_fma_f32 v18, -v17, v16, v0
	v_cmp_ge_f32_e64 s[0:1], 0, v18
	v_add_u32_e32 v18, 1, v16
	s_nop 0
	v_cndmask_b32_e64 v17, v16, v17, s[0:1]
	v_fma_f32 v16, -v18, v16, v0
	v_cmp_lt_f32_e64 s[0:1], 0, v16
	s_nop 1
	v_cndmask_b32_e64 v16, v17, v18, s[0:1]
	v_mul_f32_e32 v17, 0x37800000, v16
	v_cndmask_b32_e32 v16, v16, v17, vcc
	v_cmp_class_f32_e32 vcc, v0, v160
	s_nop 1
	v_cndmask_b32_e32 v0, v16, v0, vcc
	ds_read_b32 v16, v81 offset:9728
	s_waitcnt lgkmcnt(0)
	v_mul_f32_e32 v1, v1, v16
	v_mul_f32_e32 v0, v1, v0
	ds_write2st64_b32 v81, v2, v0 offset0:174 offset1:238
	v_add_f32_e32 v0, v85, v19
	v_mul_f32_e32 v0, 0xbfb8aa3b, v0
	v_exp_f32_e32 v0, v0
	s_nop 0
	v_add_f32_e32 v0, 1.0, v0
	s_nop 0
	v_rcp_f32_e32 v0, v0
	s_nop 0
	v_mul_f32_e32 v0, 0xc1000000, v0
	v_mul_f32_e32 v1, v0, v32
	v_fmamk_f32 v0, v1, 0x3ab60b61, v158
	v_fmaak_f32 v0, v1, v0, 0x3d2aaaab
	v_fmaak_f32 v0, v1, v0, 0x3e2aaaab
	v_fma_f32 v0, v1, v0, 0.5
	v_fma_f32 v0, v1, v0, 1.0
	v_mul_f32_e32 v0, v1, v0
	v_cmp_gt_f32_e32 vcc, s95, v1
	s_and_saveexec_b64 s[0:1], vcc
	s_cbranch_execz .LBB0_304
	v_mul_f32_e32 v0, 0x3fb8aa3b, v1
	v_rndne_f32_e32 v0, v0
	v_fmamk_f32 v2, v0, 0xbf317218, v1
	v_fmac_f32_e32 v2, 0x3102e308, v0
	v_fmamk_f32 v16, v2, 0x395133b1, v159
	v_cmp_eq_f32_e32 vcc, s96, v0
	v_cvt_i32_f32_e32 v0, v0
	v_fmaak_f32 v16, v2, v16, 0x3c0887f9
	v_fmaak_f32 v16, v2, v16, 0x3d2aaa81
	v_fmaak_f32 v16, v2, v16, 0x3e2aaaab
	v_fma_f32 v16, v2, v16, 0.5
	v_ldexp_f32 v0, 1.0, v0
	v_mul_f32_e32 v16, v2, v16
	v_cndmask_b32_e32 v0, v0, v171, vcc
	v_fmac_f32_e32 v2, v2, v16
	v_add_f32_e32 v16, -1.0, v0
	v_fmac_f32_e32 v16, v0, v2
	v_add_f32_e32 v0, v16, v16
	v_cndmask_b32_e32 v0, v16, v0, vcc
	v_cmp_ngt_f32_e32 vcc, s97, v1
	s_nop 1
	v_cndmask_b32_e32 v0, -1.0, v0, vcc
.LBB0_304:
	s_or_b64 exec, exec, s[0:1]
	v_add_f32_e32 v1, v84, v3
	v_mul_f32_e32 v1, 0xbfb8aa3b, v1
	v_exp_f32_e32 v1, v1
	s_nop 0
	v_add_f32_e32 v1, 1.0, v1
	s_nop 0
	v_add_f32_e32 v3, 2.0, v0
	v_rcp_f32_e32 v1, v1
	s_nop 0
	v_add_f32_e32 v2, 1.0, v0
	v_mul_f32_e64 v0, v3, -v0
	v_cmp_gt_f32_e32 vcc, s28, v0
	v_mul_f32_e32 v3, 0x4f800000, v0
	s_nop 0
	v_cndmask_b32_e32 v0, v0, v3, vcc
	v_sqrt_f32_e32 v3, v0
	s_nop 0
	v_add_u32_e32 v16, -1, v3
	v_fma_f32 v17, -v16, v3, v0
	v_cmp_ge_f32_e64 s[0:1], 0, v17
	v_add_u32_e32 v17, 1, v3
	s_nop 0
	v_cndmask_b32_e64 v16, v3, v16, s[0:1]
	v_fma_f32 v3, -v17, v3, v0
	v_cmp_lt_f32_e64 s[0:1], 0, v3
	s_nop 1
	v_cndmask_b32_e64 v3, v16, v17, s[0:1]
	v_mul_f32_e32 v16, 0x37800000, v3
	v_cndmask_b32_e32 v3, v3, v16, vcc
	v_cmp_class_f32_e32 vcc, v0, v160
	s_nop 1
	v_cndmask_b32_e32 v0, v3, v0, vcc
	ds_read_b32 v3, v81 offset:9984
	s_waitcnt lgkmcnt(0)
	v_mul_f32_e32 v1, v1, v3
	v_mul_f32_e32 v0, v1, v0
	ds_write2st64_b32 v81, v2, v0 offset0:175 offset1:239
	v_add_f32_e32 v0, v85, v20
	v_mul_f32_e32 v0, 0xbfb8aa3b, v0
	v_exp_f32_e32 v0, v0
	s_nop 0
	v_add_f32_e32 v0, 1.0, v0
	s_nop 0
	v_rcp_f32_e32 v0, v0
	s_nop 0
	v_mul_f32_e32 v0, 0xc1000000, v0
	v_mul_f32_e32 v1, v0, v32
	v_fmamk_f32 v0, v1, 0x3ab60b61, v158
	v_fmaak_f32 v0, v1, v0, 0x3d2aaaab
	v_fmaak_f32 v0, v1, v0, 0x3e2aaaab
	v_fma_f32 v0, v1, v0, 0.5
	v_fma_f32 v0, v1, v0, 1.0
	v_mul_f32_e32 v0, v1, v0
	v_cmp_gt_f32_e32 vcc, s95, v1
	s_and_saveexec_b64 s[0:1], vcc
	s_cbranch_execz .LBB0_306
	v_mul_f32_e32 v0, 0x3fb8aa3b, v1
	v_rndne_f32_e32 v0, v0
	v_fmamk_f32 v2, v0, 0xbf317218, v1
	v_fmac_f32_e32 v2, 0x3102e308, v0
	v_fmamk_f32 v3, v2, 0x395133b1, v159
	v_cmp_eq_f32_e32 vcc, s96, v0
	v_cvt_i32_f32_e32 v0, v0
	v_fmaak_f32 v3, v2, v3, 0x3c0887f9
	v_fmaak_f32 v3, v2, v3, 0x3d2aaa81
	v_fmaak_f32 v3, v2, v3, 0x3e2aaaab
	v_fma_f32 v3, v2, v3, 0.5
	v_ldexp_f32 v0, 1.0, v0
	v_mul_f32_e32 v3, v2, v3
	v_cndmask_b32_e32 v0, v0, v171, vcc
	v_fmac_f32_e32 v2, v2, v3
	v_add_f32_e32 v3, -1.0, v0
	v_fmac_f32_e32 v3, v0, v2
	v_add_f32_e32 v0, v3, v3
	v_cndmask_b32_e32 v0, v3, v0, vcc
	v_cmp_ngt_f32_e32 vcc, s97, v1
	s_nop 1
	v_cndmask_b32_e32 v0, -1.0, v0, vcc
.LBB0_306:
	s_or_b64 exec, exec, s[0:1]
	v_add_f32_e32 v1, v84, v4
	v_mul_f32_e32 v1, 0xbfb8aa3b, v1
	v_exp_f32_e32 v1, v1
	s_nop 0
	v_add_f32_e32 v1, 1.0, v1
	s_nop 0
	v_add_f32_e32 v3, 2.0, v0
	v_rcp_f32_e32 v1, v1
	s_nop 0
	v_add_f32_e32 v2, 1.0, v0
	v_mul_f32_e64 v0, v3, -v0
	v_cmp_gt_f32_e32 vcc, s28, v0
	v_mul_f32_e32 v3, 0x4f800000, v0
	s_nop 0
	v_cndmask_b32_e32 v0, v0, v3, vcc
	v_sqrt_f32_e32 v3, v0
	s_nop 0
	v_add_u32_e32 v4, -1, v3
	v_fma_f32 v16, -v4, v3, v0
	v_cmp_ge_f32_e64 s[0:1], 0, v16
	v_add_u32_e32 v16, 1, v3
	s_nop 0
	v_cndmask_b32_e64 v4, v3, v4, s[0:1]
	v_fma_f32 v3, -v16, v3, v0
	v_cmp_lt_f32_e64 s[0:1], 0, v3
	s_nop 1
	v_cndmask_b32_e64 v3, v4, v16, s[0:1]
	v_mul_f32_e32 v4, 0x37800000, v3
	v_cndmask_b32_e32 v3, v3, v4, vcc
	v_cmp_class_f32_e32 vcc, v0, v160
	s_nop 1
	v_cndmask_b32_e32 v0, v3, v0, vcc
	ds_read_b32 v3, v81 offset:11264
	s_waitcnt lgkmcnt(0)
	v_mul_f32_e32 v1, v1, v3
	v_mul_f32_e32 v0, v1, v0
	ds_write2st64_b32 v81, v2, v0 offset0:180 offset1:244
	v_add_f32_e32 v0, v85, v21
	v_mul_f32_e32 v0, 0xbfb8aa3b, v0
	v_exp_f32_e32 v0, v0
	s_nop 0
	v_add_f32_e32 v0, 1.0, v0
	s_nop 0
	v_rcp_f32_e32 v0, v0
	s_nop 0
	v_mul_f32_e32 v0, 0xc1000000, v0
	v_mul_f32_e32 v1, v0, v32
	v_fmamk_f32 v0, v1, 0x3ab60b61, v158
	v_fmaak_f32 v0, v1, v0, 0x3d2aaaab
	v_fmaak_f32 v0, v1, v0, 0x3e2aaaab
	v_fma_f32 v0, v1, v0, 0.5
	v_fma_f32 v0, v1, v0, 1.0
	v_mul_f32_e32 v0, v1, v0
	v_cmp_gt_f32_e32 vcc, s95, v1
	s_and_saveexec_b64 s[0:1], vcc
	s_cbranch_execz .LBB0_308
	v_mul_f32_e32 v0, 0x3fb8aa3b, v1
	v_rndne_f32_e32 v0, v0
	v_fmamk_f32 v2, v0, 0xbf317218, v1
	v_fmac_f32_e32 v2, 0x3102e308, v0
	v_fmamk_f32 v3, v2, 0x395133b1, v159
	v_cmp_eq_f32_e32 vcc, s96, v0
	v_cvt_i32_f32_e32 v0, v0
	v_fmaak_f32 v3, v2, v3, 0x3c0887f9
	v_fmaak_f32 v3, v2, v3, 0x3d2aaa81
	v_fmaak_f32 v3, v2, v3, 0x3e2aaaab
	v_fma_f32 v3, v2, v3, 0.5
	v_ldexp_f32 v0, 1.0, v0
	v_mul_f32_e32 v3, v2, v3
	v_cndmask_b32_e32 v0, v0, v171, vcc
	v_fmac_f32_e32 v2, v2, v3
	v_add_f32_e32 v3, -1.0, v0
	v_fmac_f32_e32 v3, v0, v2
	v_add_f32_e32 v0, v3, v3
	v_cndmask_b32_e32 v0, v3, v0, vcc
	v_cmp_ngt_f32_e32 vcc, s97, v1
	s_nop 1
	v_cndmask_b32_e32 v0, -1.0, v0, vcc
.LBB0_308:
	s_or_b64 exec, exec, s[0:1]
	v_add_f32_e32 v1, v84, v5
	v_mul_f32_e32 v1, 0xbfb8aa3b, v1
	v_exp_f32_e32 v1, v1
	s_nop 0
	v_add_f32_e32 v1, 1.0, v1
	s_nop 0
	v_add_f32_e32 v3, 2.0, v0
	v_rcp_f32_e32 v1, v1
	s_nop 0
	v_add_f32_e32 v2, 1.0, v0
	v_mul_f32_e64 v0, v3, -v0
	v_cmp_gt_f32_e32 vcc, s28, v0
	v_mul_f32_e32 v3, 0x4f800000, v0
	s_nop 0
	v_cndmask_b32_e32 v0, v0, v3, vcc
	v_sqrt_f32_e32 v3, v0
	s_nop 0
	v_add_u32_e32 v4, -1, v3
	v_fma_f32 v5, -v4, v3, v0
	v_cmp_ge_f32_e64 s[0:1], 0, v5
	v_add_u32_e32 v5, 1, v3
	s_nop 0
	v_cndmask_b32_e64 v4, v3, v4, s[0:1]
	v_fma_f32 v3, -v5, v3, v0
	v_cmp_lt_f32_e64 s[0:1], 0, v3
	s_nop 1
	v_cndmask_b32_e64 v3, v4, v5, s[0:1]
	v_mul_f32_e32 v4, 0x37800000, v3
	v_cndmask_b32_e32 v3, v3, v4, vcc
	v_cmp_class_f32_e32 vcc, v0, v160
	s_nop 1
	v_cndmask_b32_e32 v0, v3, v0, vcc
	ds_read_b32 v3, v81 offset:11520
	s_waitcnt lgkmcnt(0)
	v_mul_f32_e32 v1, v1, v3
	v_mul_f32_e32 v0, v1, v0
	ds_write2st64_b32 v81, v2, v0 offset0:181 offset1:245
	v_add_f32_e32 v0, v85, v22
	v_mul_f32_e32 v0, 0xbfb8aa3b, v0
	v_exp_f32_e32 v0, v0
	s_nop 0
	v_add_f32_e32 v0, 1.0, v0
	s_nop 0
	v_rcp_f32_e32 v0, v0
	s_nop 0
	v_mul_f32_e32 v0, 0xc1000000, v0
	v_mul_f32_e32 v1, v0, v32
	v_fmamk_f32 v0, v1, 0x3ab60b61, v158
	v_fmaak_f32 v0, v1, v0, 0x3d2aaaab
	v_fmaak_f32 v0, v1, v0, 0x3e2aaaab
	v_fma_f32 v0, v1, v0, 0.5
	v_fma_f32 v0, v1, v0, 1.0
	v_mul_f32_e32 v0, v1, v0
	v_cmp_gt_f32_e32 vcc, s95, v1
	s_and_saveexec_b64 s[0:1], vcc
	s_cbranch_execz .LBB0_310
	v_mul_f32_e32 v0, 0x3fb8aa3b, v1
	v_rndne_f32_e32 v0, v0
	v_fmamk_f32 v2, v0, 0xbf317218, v1
	v_fmac_f32_e32 v2, 0x3102e308, v0
	v_fmamk_f32 v3, v2, 0x395133b1, v159
	v_cmp_eq_f32_e32 vcc, s96, v0
	v_cvt_i32_f32_e32 v0, v0
	v_fmaak_f32 v3, v2, v3, 0x3c0887f9
	v_fmaak_f32 v3, v2, v3, 0x3d2aaa81
	v_fmaak_f32 v3, v2, v3, 0x3e2aaaab
	v_fma_f32 v3, v2, v3, 0.5
	v_ldexp_f32 v0, 1.0, v0
	v_mul_f32_e32 v3, v2, v3
	v_cndmask_b32_e32 v0, v0, v171, vcc
	v_fmac_f32_e32 v2, v2, v3
	v_add_f32_e32 v3, -1.0, v0
	v_fmac_f32_e32 v3, v0, v2
	v_add_f32_e32 v0, v3, v3
	v_cndmask_b32_e32 v0, v3, v0, vcc
	v_cmp_ngt_f32_e32 vcc, s97, v1
	s_nop 1
	v_cndmask_b32_e32 v0, -1.0, v0, vcc
.LBB0_310:
	s_or_b64 exec, exec, s[0:1]
	v_add_f32_e32 v1, v84, v6
	v_mul_f32_e32 v1, 0xbfb8aa3b, v1
	v_exp_f32_e32 v1, v1
	s_nop 0
	v_add_f32_e32 v1, 1.0, v1
	s_nop 0
	v_add_f32_e32 v3, 2.0, v0
	v_rcp_f32_e32 v1, v1
	s_nop 0
	v_add_f32_e32 v2, 1.0, v0
	v_mul_f32_e64 v0, v3, -v0
	v_cmp_gt_f32_e32 vcc, s28, v0
	v_mul_f32_e32 v3, 0x4f800000, v0
	s_nop 0
	v_cndmask_b32_e32 v0, v0, v3, vcc
	v_sqrt_f32_e32 v3, v0
	s_nop 0
	v_add_u32_e32 v4, -1, v3
	v_fma_f32 v5, -v4, v3, v0
	v_cmp_ge_f32_e64 s[0:1], 0, v5
	v_add_u32_e32 v5, 1, v3
	s_nop 0
	v_cndmask_b32_e64 v4, v3, v4, s[0:1]
	v_fma_f32 v3, -v5, v3, v0
	v_cmp_lt_f32_e64 s[0:1], 0, v3
	s_nop 1
	v_cndmask_b32_e64 v3, v4, v5, s[0:1]
	v_mul_f32_e32 v4, 0x37800000, v3
	v_cndmask_b32_e32 v3, v3, v4, vcc
	v_cmp_class_f32_e32 vcc, v0, v160
	s_nop 1
	v_cndmask_b32_e32 v0, v3, v0, vcc
	ds_read_b32 v3, v81 offset:11776
	s_waitcnt lgkmcnt(0)
	v_mul_f32_e32 v1, v1, v3
	v_mul_f32_e32 v0, v1, v0
	ds_write2st64_b32 v81, v2, v0 offset0:182 offset1:246
	v_add_f32_e32 v0, v85, v23
	v_mul_f32_e32 v0, 0xbfb8aa3b, v0
	v_exp_f32_e32 v0, v0
	s_nop 0
	v_add_f32_e32 v0, 1.0, v0
	s_nop 0
	v_rcp_f32_e32 v0, v0
	s_nop 0
	v_mul_f32_e32 v0, 0xc1000000, v0
	v_mul_f32_e32 v1, v0, v32
	v_fmamk_f32 v0, v1, 0x3ab60b61, v158
	v_fmaak_f32 v0, v1, v0, 0x3d2aaaab
	v_fmaak_f32 v0, v1, v0, 0x3e2aaaab
	v_fma_f32 v0, v1, v0, 0.5
	v_fma_f32 v0, v1, v0, 1.0
	v_mul_f32_e32 v0, v1, v0
	v_cmp_gt_f32_e32 vcc, s95, v1
	s_and_saveexec_b64 s[0:1], vcc
	s_cbranch_execz .LBB0_312
	v_mul_f32_e32 v0, 0x3fb8aa3b, v1
	v_rndne_f32_e32 v0, v0
	v_fmamk_f32 v2, v0, 0xbf317218, v1
	v_fmac_f32_e32 v2, 0x3102e308, v0
	v_fmamk_f32 v3, v2, 0x395133b1, v159
	v_cmp_eq_f32_e32 vcc, s96, v0
	v_cvt_i32_f32_e32 v0, v0
	v_fmaak_f32 v3, v2, v3, 0x3c0887f9
	v_fmaak_f32 v3, v2, v3, 0x3d2aaa81
	v_fmaak_f32 v3, v2, v3, 0x3e2aaaab
	v_fma_f32 v3, v2, v3, 0.5
	v_ldexp_f32 v0, 1.0, v0
	v_mul_f32_e32 v3, v2, v3
	v_cndmask_b32_e32 v0, v0, v171, vcc
	v_fmac_f32_e32 v2, v2, v3
	v_add_f32_e32 v3, -1.0, v0
	v_fmac_f32_e32 v3, v0, v2
	v_add_f32_e32 v0, v3, v3
	v_cndmask_b32_e32 v0, v3, v0, vcc
	v_cmp_ngt_f32_e32 vcc, s97, v1
	s_nop 1
	v_cndmask_b32_e32 v0, -1.0, v0, vcc
.LBB0_312:
	s_or_b64 exec, exec, s[0:1]
	v_add_f32_e32 v1, v84, v7
	v_mul_f32_e32 v1, 0xbfb8aa3b, v1
	v_exp_f32_e32 v1, v1
	s_nop 0
	v_add_f32_e32 v1, 1.0, v1
	s_nop 0
	v_add_f32_e32 v3, 2.0, v0
	v_rcp_f32_e32 v1, v1
	s_nop 0
	v_add_f32_e32 v2, 1.0, v0
	v_mul_f32_e64 v0, v3, -v0
	v_cmp_gt_f32_e32 vcc, s28, v0
	v_mul_f32_e32 v3, 0x4f800000, v0
	s_nop 0
	v_cndmask_b32_e32 v0, v0, v3, vcc
	v_sqrt_f32_e32 v3, v0
	s_nop 0
	v_add_u32_e32 v4, -1, v3
	v_fma_f32 v5, -v4, v3, v0
	v_cmp_ge_f32_e64 s[0:1], 0, v5
	v_add_u32_e32 v5, 1, v3
	s_nop 0
	v_cndmask_b32_e64 v4, v3, v4, s[0:1]
	v_fma_f32 v3, -v5, v3, v0
	v_cmp_lt_f32_e64 s[0:1], 0, v3
	s_nop 1
	v_cndmask_b32_e64 v3, v4, v5, s[0:1]
	v_mul_f32_e32 v4, 0x37800000, v3
	v_cndmask_b32_e32 v3, v3, v4, vcc
	v_cmp_class_f32_e32 vcc, v0, v160
	s_nop 1
	v_cndmask_b32_e32 v0, v3, v0, vcc
	ds_read_b32 v3, v81 offset:12032
	s_waitcnt lgkmcnt(0)
	v_mul_f32_e32 v1, v1, v3
	v_mul_f32_e32 v0, v1, v0
	ds_write2st64_b32 v81, v2, v0 offset0:183 offset1:247
	v_add_f32_e32 v0, v85, v24
	v_mul_f32_e32 v0, 0xbfb8aa3b, v0
	v_exp_f32_e32 v0, v0
	s_nop 0
	v_add_f32_e32 v0, 1.0, v0
	s_nop 0
	v_rcp_f32_e32 v0, v0
	s_nop 0
	v_mul_f32_e32 v0, 0xc1000000, v0
	v_mul_f32_e32 v1, v0, v32
	v_fmamk_f32 v0, v1, 0x3ab60b61, v158
	v_fmaak_f32 v0, v1, v0, 0x3d2aaaab
	v_fmaak_f32 v0, v1, v0, 0x3e2aaaab
	v_fma_f32 v0, v1, v0, 0.5
	v_fma_f32 v0, v1, v0, 1.0
	v_mul_f32_e32 v0, v1, v0
	v_cmp_gt_f32_e32 vcc, s95, v1
	s_and_saveexec_b64 s[0:1], vcc
	s_cbranch_execz .LBB0_314
	v_mul_f32_e32 v0, 0x3fb8aa3b, v1
	v_rndne_f32_e32 v0, v0
	v_fmamk_f32 v2, v0, 0xbf317218, v1
	v_fmac_f32_e32 v2, 0x3102e308, v0
	v_fmamk_f32 v3, v2, 0x395133b1, v159
	v_cmp_eq_f32_e32 vcc, s96, v0
	v_cvt_i32_f32_e32 v0, v0
	v_fmaak_f32 v3, v2, v3, 0x3c0887f9
	v_fmaak_f32 v3, v2, v3, 0x3d2aaa81
	v_fmaak_f32 v3, v2, v3, 0x3e2aaaab
	v_fma_f32 v3, v2, v3, 0.5
	v_ldexp_f32 v0, 1.0, v0
	v_mul_f32_e32 v3, v2, v3
	v_cndmask_b32_e32 v0, v0, v171, vcc
	v_fmac_f32_e32 v2, v2, v3
	v_add_f32_e32 v3, -1.0, v0
	v_fmac_f32_e32 v3, v0, v2
	v_add_f32_e32 v0, v3, v3
	v_cndmask_b32_e32 v0, v3, v0, vcc
	v_cmp_ngt_f32_e32 vcc, s97, v1
	s_nop 1
	v_cndmask_b32_e32 v0, -1.0, v0, vcc
.LBB0_314:
	s_or_b64 exec, exec, s[0:1]
	v_add_f32_e32 v1, v84, v8
	v_mul_f32_e32 v1, 0xbfb8aa3b, v1
	v_exp_f32_e32 v1, v1
	s_nop 0
	v_add_f32_e32 v1, 1.0, v1
	s_nop 0
	v_add_f32_e32 v3, 2.0, v0
	v_rcp_f32_e32 v1, v1
	s_nop 0
	v_add_f32_e32 v2, 1.0, v0
	v_mul_f32_e64 v0, v3, -v0
	v_cmp_gt_f32_e32 vcc, s28, v0
	v_mul_f32_e32 v3, 0x4f800000, v0
	s_nop 0
	v_cndmask_b32_e32 v0, v0, v3, vcc
	v_sqrt_f32_e32 v3, v0
	s_nop 0
	v_add_u32_e32 v4, -1, v3
	v_fma_f32 v5, -v4, v3, v0
	v_cmp_ge_f32_e64 s[0:1], 0, v5
	v_add_u32_e32 v5, 1, v3
	s_nop 0
	v_cndmask_b32_e64 v4, v3, v4, s[0:1]
	v_fma_f32 v3, -v5, v3, v0
	v_cmp_lt_f32_e64 s[0:1], 0, v3
	s_nop 1
	v_cndmask_b32_e64 v3, v4, v5, s[0:1]
	v_mul_f32_e32 v4, 0x37800000, v3
	v_cndmask_b32_e32 v3, v3, v4, vcc
	v_cmp_class_f32_e32 vcc, v0, v160
	s_nop 1
	v_cndmask_b32_e32 v0, v3, v0, vcc
	ds_read_b32 v3, v81 offset:13312
	s_waitcnt lgkmcnt(0)
	v_mul_f32_e32 v1, v1, v3
	v_mul_f32_e32 v0, v1, v0
	ds_write2st64_b32 v81, v2, v0 offset0:188 offset1:252
	v_add_f32_e32 v0, v85, v25
	v_mul_f32_e32 v0, 0xbfb8aa3b, v0
	v_exp_f32_e32 v0, v0
	s_nop 0
	v_add_f32_e32 v0, 1.0, v0
	s_nop 0
	v_rcp_f32_e32 v0, v0
	s_nop 0
	v_mul_f32_e32 v0, 0xc1000000, v0
	v_mul_f32_e32 v1, v0, v32
	v_fmamk_f32 v0, v1, 0x3ab60b61, v158
	v_fmaak_f32 v0, v1, v0, 0x3d2aaaab
	v_fmaak_f32 v0, v1, v0, 0x3e2aaaab
	v_fma_f32 v0, v1, v0, 0.5
	v_fma_f32 v0, v1, v0, 1.0
	v_mul_f32_e32 v0, v1, v0
	v_cmp_gt_f32_e32 vcc, s95, v1
	s_and_saveexec_b64 s[0:1], vcc
	s_cbranch_execz .LBB0_316
	v_mul_f32_e32 v0, 0x3fb8aa3b, v1
	v_rndne_f32_e32 v0, v0
	v_fmamk_f32 v2, v0, 0xbf317218, v1
	v_fmac_f32_e32 v2, 0x3102e308, v0
	v_fmamk_f32 v3, v2, 0x395133b1, v159
	v_cmp_eq_f32_e32 vcc, s96, v0
	v_cvt_i32_f32_e32 v0, v0
	v_fmaak_f32 v3, v2, v3, 0x3c0887f9
	v_fmaak_f32 v3, v2, v3, 0x3d2aaa81
	v_fmaak_f32 v3, v2, v3, 0x3e2aaaab
	v_fma_f32 v3, v2, v3, 0.5
	v_ldexp_f32 v0, 1.0, v0
	v_mul_f32_e32 v3, v2, v3
	v_cndmask_b32_e32 v0, v0, v171, vcc
	v_fmac_f32_e32 v2, v2, v3
	v_add_f32_e32 v3, -1.0, v0
	v_fmac_f32_e32 v3, v0, v2
	v_add_f32_e32 v0, v3, v3
	v_cndmask_b32_e32 v0, v3, v0, vcc
	v_cmp_ngt_f32_e32 vcc, s97, v1
	s_nop 1
	v_cndmask_b32_e32 v0, -1.0, v0, vcc
.LBB0_316:
	s_or_b64 exec, exec, s[0:1]
	v_add_f32_e32 v1, v84, v9
	v_mul_f32_e32 v1, 0xbfb8aa3b, v1
	v_exp_f32_e32 v1, v1
	s_nop 0
	v_add_f32_e32 v1, 1.0, v1
	s_nop 0
	v_add_f32_e32 v3, 2.0, v0
	v_rcp_f32_e32 v1, v1
	s_nop 0
	v_add_f32_e32 v2, 1.0, v0
	v_mul_f32_e64 v0, v3, -v0
	v_cmp_gt_f32_e32 vcc, s28, v0
	v_mul_f32_e32 v3, 0x4f800000, v0
	s_nop 0
	v_cndmask_b32_e32 v0, v0, v3, vcc
	v_sqrt_f32_e32 v3, v0
	s_nop 0
	v_add_u32_e32 v4, -1, v3
	v_fma_f32 v5, -v4, v3, v0
	v_cmp_ge_f32_e64 s[0:1], 0, v5
	v_add_u32_e32 v5, 1, v3
	s_nop 0
	v_cndmask_b32_e64 v4, v3, v4, s[0:1]
	v_fma_f32 v3, -v5, v3, v0
	v_cmp_lt_f32_e64 s[0:1], 0, v3
	s_nop 1
	v_cndmask_b32_e64 v3, v4, v5, s[0:1]
	v_mul_f32_e32 v4, 0x37800000, v3
	v_cndmask_b32_e32 v3, v3, v4, vcc
	v_cmp_class_f32_e32 vcc, v0, v160
	s_nop 1
	v_cndmask_b32_e32 v0, v3, v0, vcc
	ds_read_b32 v3, v81 offset:13568
	s_waitcnt lgkmcnt(0)
	v_mul_f32_e32 v1, v1, v3
	v_mul_f32_e32 v0, v1, v0
	ds_write2st64_b32 v81, v2, v0 offset0:189 offset1:253
	v_add_f32_e32 v0, v85, v26
	v_mul_f32_e32 v0, 0xbfb8aa3b, v0
	v_exp_f32_e32 v0, v0
	s_nop 0
	v_add_f32_e32 v0, 1.0, v0
	s_nop 0
	v_rcp_f32_e32 v0, v0
	s_nop 0
	v_mul_f32_e32 v0, 0xc1000000, v0
	v_mul_f32_e32 v1, v0, v32
	v_fmamk_f32 v0, v1, 0x3ab60b61, v158
	v_fmaak_f32 v0, v1, v0, 0x3d2aaaab
	v_fmaak_f32 v0, v1, v0, 0x3e2aaaab
	v_fma_f32 v0, v1, v0, 0.5
	v_fma_f32 v0, v1, v0, 1.0
	v_mul_f32_e32 v0, v1, v0
	v_cmp_gt_f32_e32 vcc, s95, v1
	s_and_saveexec_b64 s[0:1], vcc
	s_cbranch_execz .LBB0_318
	v_mul_f32_e32 v0, 0x3fb8aa3b, v1
	v_rndne_f32_e32 v0, v0
	v_fmamk_f32 v2, v0, 0xbf317218, v1
	v_fmac_f32_e32 v2, 0x3102e308, v0
	v_fmamk_f32 v3, v2, 0x395133b1, v159
	v_cmp_eq_f32_e32 vcc, s96, v0
	v_cvt_i32_f32_e32 v0, v0
	v_fmaak_f32 v3, v2, v3, 0x3c0887f9
	v_fmaak_f32 v3, v2, v3, 0x3d2aaa81
	v_fmaak_f32 v3, v2, v3, 0x3e2aaaab
	v_fma_f32 v3, v2, v3, 0.5
	v_ldexp_f32 v0, 1.0, v0
	v_mul_f32_e32 v3, v2, v3
	v_cndmask_b32_e32 v0, v0, v171, vcc
	v_fmac_f32_e32 v2, v2, v3
	v_add_f32_e32 v3, -1.0, v0
	v_fmac_f32_e32 v3, v0, v2
	v_add_f32_e32 v0, v3, v3
	v_cndmask_b32_e32 v0, v3, v0, vcc
	v_cmp_ngt_f32_e32 vcc, s97, v1
	s_nop 1
	v_cndmask_b32_e32 v0, -1.0, v0, vcc
.LBB0_318:
	s_or_b64 exec, exec, s[0:1]
	v_add_f32_e32 v1, v84, v10
	v_mul_f32_e32 v1, 0xbfb8aa3b, v1
	v_exp_f32_e32 v1, v1
	s_nop 0
	v_add_f32_e32 v1, 1.0, v1
	s_nop 0
	v_add_f32_e32 v3, 2.0, v0
	v_rcp_f32_e32 v1, v1
	s_nop 0
	v_add_f32_e32 v2, 1.0, v0
	v_mul_f32_e64 v0, v3, -v0
	v_cmp_gt_f32_e32 vcc, s28, v0
	v_mul_f32_e32 v3, 0x4f800000, v0
	s_nop 0
	v_cndmask_b32_e32 v0, v0, v3, vcc
	v_sqrt_f32_e32 v3, v0
	s_nop 0
	v_add_u32_e32 v4, -1, v3
	v_fma_f32 v5, -v4, v3, v0
	v_cmp_ge_f32_e64 s[0:1], 0, v5
	v_add_u32_e32 v5, 1, v3
	s_nop 0
	v_cndmask_b32_e64 v4, v3, v4, s[0:1]
	v_fma_f32 v3, -v5, v3, v0
	v_cmp_lt_f32_e64 s[0:1], 0, v3
	s_nop 1
	v_cndmask_b32_e64 v3, v4, v5, s[0:1]
	v_mul_f32_e32 v4, 0x37800000, v3
	v_cndmask_b32_e32 v3, v3, v4, vcc
	v_cmp_class_f32_e32 vcc, v0, v160
	s_nop 1
	v_cndmask_b32_e32 v0, v3, v0, vcc
	ds_read_b32 v3, v81 offset:13824
	s_waitcnt lgkmcnt(0)
	v_mul_f32_e32 v1, v1, v3
	v_mul_f32_e32 v0, v1, v0
	ds_write2st64_b32 v81, v2, v0 offset0:190 offset1:254
	v_add_f32_e32 v0, v85, v27
	v_mul_f32_e32 v0, 0xbfb8aa3b, v0
	v_exp_f32_e32 v0, v0
	s_nop 0
	v_add_f32_e32 v0, 1.0, v0
	s_nop 0
	v_rcp_f32_e32 v0, v0
	s_nop 0
	v_mul_f32_e32 v0, 0xc1000000, v0
	v_mul_f32_e32 v1, v0, v32
	v_fmamk_f32 v0, v1, 0x3ab60b61, v158
	v_fmaak_f32 v0, v1, v0, 0x3d2aaaab
	v_fmaak_f32 v0, v1, v0, 0x3e2aaaab
	v_fma_f32 v0, v1, v0, 0.5
	v_fma_f32 v0, v1, v0, 1.0
	v_mul_f32_e32 v0, v1, v0
	v_cmp_gt_f32_e32 vcc, s95, v1
	s_and_saveexec_b64 s[0:1], vcc
	s_cbranch_execz .LBB0_320
	v_mul_f32_e32 v0, 0x3fb8aa3b, v1
	v_rndne_f32_e32 v0, v0
	v_fmamk_f32 v2, v0, 0xbf317218, v1
	v_fmac_f32_e32 v2, 0x3102e308, v0
	v_fmamk_f32 v3, v2, 0x395133b1, v159
	v_cmp_eq_f32_e32 vcc, s96, v0
	v_cvt_i32_f32_e32 v0, v0
	v_fmaak_f32 v3, v2, v3, 0x3c0887f9
	v_fmaak_f32 v3, v2, v3, 0x3d2aaa81
	v_fmaak_f32 v3, v2, v3, 0x3e2aaaab
	v_fma_f32 v3, v2, v3, 0.5
	v_ldexp_f32 v0, 1.0, v0
	v_mul_f32_e32 v3, v2, v3
	v_cndmask_b32_e32 v0, v0, v171, vcc
	v_fmac_f32_e32 v2, v2, v3
	v_add_f32_e32 v3, -1.0, v0
	v_fmac_f32_e32 v3, v0, v2
	v_add_f32_e32 v0, v3, v3
	v_cndmask_b32_e32 v0, v3, v0, vcc
	v_cmp_ngt_f32_e32 vcc, s97, v1
	s_nop 1
	v_cndmask_b32_e32 v0, -1.0, v0, vcc
.LBB0_320:
	s_or_b64 exec, exec, s[0:1]
	v_add_f32_e32 v1, v84, v11
	v_mul_f32_e32 v1, 0xbfb8aa3b, v1
	v_exp_f32_e32 v1, v1
	s_nop 0
	v_add_f32_e32 v1, 1.0, v1
	s_nop 0
	v_add_f32_e32 v3, 2.0, v0
	v_rcp_f32_e32 v1, v1
	s_nop 0
	v_add_f32_e32 v2, 1.0, v0
	v_mul_f32_e64 v0, v3, -v0
	v_cmp_gt_f32_e32 vcc, s28, v0
	v_mul_f32_e32 v3, 0x4f800000, v0
	s_nop 0
	v_cndmask_b32_e32 v0, v0, v3, vcc
	v_sqrt_f32_e32 v3, v0
	s_nop 0
	v_add_u32_e32 v4, -1, v3
	v_fma_f32 v5, -v4, v3, v0
	v_cmp_ge_f32_e64 s[0:1], 0, v5
	v_add_u32_e32 v5, 1, v3
	s_nop 0
	v_cndmask_b32_e64 v4, v3, v4, s[0:1]
	v_fma_f32 v3, -v5, v3, v0
	v_cmp_lt_f32_e64 s[0:1], 0, v3
	s_nop 1
	v_cndmask_b32_e64 v3, v4, v5, s[0:1]
	v_mul_f32_e32 v4, 0x37800000, v3
	v_cndmask_b32_e32 v3, v3, v4, vcc
	v_cmp_class_f32_e32 vcc, v0, v160
	s_nop 1
	v_cndmask_b32_e32 v0, v3, v0, vcc
	ds_read_b32 v3, v81 offset:14080
	s_waitcnt lgkmcnt(0)
	v_mul_f32_e32 v1, v1, v3
	v_mul_f32_e32 v0, v1, v0
	ds_write2st64_b32 v81, v2, v0 offset0:191 offset1:255
	v_add_f32_e32 v0, v85, v28
	v_mul_f32_e32 v0, 0xbfb8aa3b, v0
	v_exp_f32_e32 v0, v0
	s_nop 0
	v_add_f32_e32 v0, 1.0, v0
	s_nop 0
	v_rcp_f32_e32 v0, v0
	s_nop 0
	v_mul_f32_e32 v0, 0xc1000000, v0
	v_mul_f32_e32 v1, v0, v32
	v_fmamk_f32 v0, v1, 0x3ab60b61, v158
	v_fmaak_f32 v0, v1, v0, 0x3d2aaaab
	v_fmaak_f32 v0, v1, v0, 0x3e2aaaab
	v_fma_f32 v0, v1, v0, 0.5
	v_fma_f32 v0, v1, v0, 1.0
	v_mul_f32_e32 v0, v1, v0
	v_cmp_gt_f32_e32 vcc, s95, v1
	s_and_saveexec_b64 s[0:1], vcc
	s_cbranch_execz .LBB0_322
	v_mul_f32_e32 v0, 0x3fb8aa3b, v1
	v_rndne_f32_e32 v0, v0
	v_fmamk_f32 v2, v0, 0xbf317218, v1
	v_fmac_f32_e32 v2, 0x3102e308, v0
	v_fmamk_f32 v3, v2, 0x395133b1, v159
	v_cmp_eq_f32_e32 vcc, s96, v0
	v_cvt_i32_f32_e32 v0, v0
	v_fmaak_f32 v3, v2, v3, 0x3c0887f9
	v_fmaak_f32 v3, v2, v3, 0x3d2aaa81
	v_fmaak_f32 v3, v2, v3, 0x3e2aaaab
	v_fma_f32 v3, v2, v3, 0.5
	v_ldexp_f32 v0, 1.0, v0
	v_mul_f32_e32 v3, v2, v3
	v_cndmask_b32_e32 v0, v0, v171, vcc
	v_fmac_f32_e32 v2, v2, v3
	v_add_f32_e32 v3, -1.0, v0
	v_fmac_f32_e32 v3, v0, v2
	v_add_f32_e32 v0, v3, v3
	v_cndmask_b32_e32 v0, v3, v0, vcc
	v_cmp_ngt_f32_e32 vcc, s97, v1
	s_nop 1
	v_cndmask_b32_e32 v0, -1.0, v0, vcc
.LBB0_322:
	s_or_b64 exec, exec, s[0:1]
	v_add_f32_e32 v1, v84, v12
	v_mul_f32_e32 v1, 0xbfb8aa3b, v1
	v_exp_f32_e32 v1, v1
	s_nop 0
	v_add_f32_e32 v1, 1.0, v1
	s_nop 0
	v_add_f32_e32 v3, 2.0, v0
	v_rcp_f32_e32 v1, v1
	s_nop 0
	v_add_f32_e32 v2, 1.0, v0
	v_mul_f32_e64 v0, v3, -v0
	v_cmp_gt_f32_e32 vcc, s28, v0
	v_mul_f32_e32 v3, 0x4f800000, v0
	s_nop 0
	v_cndmask_b32_e32 v0, v0, v3, vcc
	v_sqrt_f32_e32 v3, v0
	s_nop 0
	v_add_u32_e32 v4, -1, v3
	v_fma_f32 v5, -v4, v3, v0
	v_cmp_ge_f32_e64 s[0:1], 0, v5
	v_add_u32_e32 v5, 1, v3
	s_nop 0
	v_cndmask_b32_e64 v4, v3, v4, s[0:1]
	v_fma_f32 v3, -v5, v3, v0
	v_cmp_lt_f32_e64 s[0:1], 0, v3
	s_nop 1
	v_cndmask_b32_e64 v3, v4, v5, s[0:1]
	v_mul_f32_e32 v4, 0x37800000, v3
	v_cndmask_b32_e32 v3, v3, v4, vcc
	v_cmp_class_f32_e32 vcc, v0, v160
	s_nop 1
	v_cndmask_b32_e32 v0, v3, v0, vcc
	ds_read_b32 v3, v81 offset:15360
	s_waitcnt lgkmcnt(0)
	v_mul_f32_e32 v1, v1, v3
	v_mul_f32_e32 v0, v1, v0
	ds_write_b32 v81, v2 offset:50176
	ds_write_b32 v95, v0
	v_add_f32_e32 v0, v85, v29
	v_mul_f32_e32 v0, 0xbfb8aa3b, v0
	v_exp_f32_e32 v0, v0
	s_nop 0
	v_add_f32_e32 v0, 1.0, v0
	s_nop 0
	v_rcp_f32_e32 v0, v0
	s_nop 0
	v_mul_f32_e32 v0, 0xc1000000, v0
	v_mul_f32_e32 v1, v0, v32
	v_fmamk_f32 v0, v1, 0x3ab60b61, v158
	v_fmaak_f32 v0, v1, v0, 0x3d2aaaab
	v_fmaak_f32 v0, v1, v0, 0x3e2aaaab
	v_fma_f32 v0, v1, v0, 0.5
	v_fma_f32 v0, v1, v0, 1.0
	v_mul_f32_e32 v0, v1, v0
	v_cmp_gt_f32_e32 vcc, s95, v1
	s_and_saveexec_b64 s[0:1], vcc
	s_cbranch_execz .LBB0_324
	v_mul_f32_e32 v0, 0x3fb8aa3b, v1
	v_rndne_f32_e32 v0, v0
	v_fmamk_f32 v2, v0, 0xbf317218, v1
	v_fmac_f32_e32 v2, 0x3102e308, v0
	v_fmamk_f32 v3, v2, 0x395133b1, v159
	v_cmp_eq_f32_e32 vcc, s96, v0
	v_cvt_i32_f32_e32 v0, v0
	v_fmaak_f32 v3, v2, v3, 0x3c0887f9
	v_fmaak_f32 v3, v2, v3, 0x3d2aaa81
	v_fmaak_f32 v3, v2, v3, 0x3e2aaaab
	v_fma_f32 v3, v2, v3, 0.5
	v_ldexp_f32 v0, 1.0, v0
	v_mul_f32_e32 v3, v2, v3
	v_cndmask_b32_e32 v0, v0, v171, vcc
	v_fmac_f32_e32 v2, v2, v3
	v_add_f32_e32 v3, -1.0, v0
	v_fmac_f32_e32 v3, v0, v2
	v_add_f32_e32 v0, v3, v3
	v_cndmask_b32_e32 v0, v3, v0, vcc
	v_cmp_ngt_f32_e32 vcc, s97, v1
	s_nop 1
	v_cndmask_b32_e32 v0, -1.0, v0, vcc
.LBB0_324:
	s_or_b64 exec, exec, s[0:1]
	v_add_f32_e32 v1, v84, v13
	v_mul_f32_e32 v1, 0xbfb8aa3b, v1
	v_exp_f32_e32 v1, v1
	s_nop 0
	v_add_f32_e32 v1, 1.0, v1
	s_nop 0
	v_add_f32_e32 v3, 2.0, v0
	v_rcp_f32_e32 v1, v1
	s_nop 0
	v_add_f32_e32 v2, 1.0, v0
	v_mul_f32_e64 v0, v3, -v0
	v_cmp_gt_f32_e32 vcc, s28, v0
	v_mul_f32_e32 v3, 0x4f800000, v0
	s_nop 0
	v_cndmask_b32_e32 v0, v0, v3, vcc
	v_sqrt_f32_e32 v3, v0
	s_nop 0
	v_add_u32_e32 v4, -1, v3
	v_fma_f32 v5, -v4, v3, v0
	v_cmp_ge_f32_e64 s[0:1], 0, v5
	v_add_u32_e32 v5, 1, v3
	s_nop 0
	v_cndmask_b32_e64 v4, v3, v4, s[0:1]
	v_fma_f32 v3, -v5, v3, v0
	v_cmp_lt_f32_e64 s[0:1], 0, v3
	s_nop 1
	v_cndmask_b32_e64 v3, v4, v5, s[0:1]
	v_mul_f32_e32 v4, 0x37800000, v3
	v_cndmask_b32_e32 v3, v3, v4, vcc
	v_cmp_class_f32_e32 vcc, v0, v160
	s_nop 1
	v_cndmask_b32_e32 v0, v3, v0, vcc
	ds_read_b32 v3, v81 offset:15616
	s_waitcnt lgkmcnt(0)
	v_mul_f32_e32 v1, v1, v3
	v_mul_f32_e32 v0, v1, v0
	ds_write_b32 v81, v2 offset:50432
	ds_write_b32 v97, v0
	v_add_f32_e32 v0, v85, v30
	v_mul_f32_e32 v0, 0xbfb8aa3b, v0
	v_exp_f32_e32 v0, v0
	s_nop 0
	v_add_f32_e32 v0, 1.0, v0
	s_nop 0
	v_rcp_f32_e32 v0, v0
	s_nop 0
	v_mul_f32_e32 v0, 0xc1000000, v0
	v_mul_f32_e32 v1, v0, v32
	v_fmamk_f32 v0, v1, 0x3ab60b61, v158
	v_fmaak_f32 v0, v1, v0, 0x3d2aaaab
	v_fmaak_f32 v0, v1, v0, 0x3e2aaaab
	v_fma_f32 v0, v1, v0, 0.5
	v_fma_f32 v0, v1, v0, 1.0
	v_mul_f32_e32 v0, v1, v0
	v_cmp_gt_f32_e32 vcc, s95, v1
	s_and_saveexec_b64 s[0:1], vcc
	s_cbranch_execz .LBB0_326
	v_mul_f32_e32 v0, 0x3fb8aa3b, v1
	v_rndne_f32_e32 v0, v0
	v_fmamk_f32 v2, v0, 0xbf317218, v1
	v_fmac_f32_e32 v2, 0x3102e308, v0
	v_fmamk_f32 v3, v2, 0x395133b1, v159
	v_cmp_eq_f32_e32 vcc, s96, v0
	v_cvt_i32_f32_e32 v0, v0
	v_fmaak_f32 v3, v2, v3, 0x3c0887f9
	v_fmaak_f32 v3, v2, v3, 0x3d2aaa81
	v_fmaak_f32 v3, v2, v3, 0x3e2aaaab
	v_fma_f32 v3, v2, v3, 0.5
	v_ldexp_f32 v0, 1.0, v0
	v_mul_f32_e32 v3, v2, v3
	v_cndmask_b32_e32 v0, v0, v171, vcc
	v_fmac_f32_e32 v2, v2, v3
	v_add_f32_e32 v3, -1.0, v0
	v_fmac_f32_e32 v3, v0, v2
	v_add_f32_e32 v0, v3, v3
	v_cndmask_b32_e32 v0, v3, v0, vcc
	v_cmp_ngt_f32_e32 vcc, s97, v1
	s_nop 1
	v_cndmask_b32_e32 v0, -1.0, v0, vcc
.LBB0_326:
	s_or_b64 exec, exec, s[0:1]
	v_add_f32_e32 v1, v84, v14
	v_mul_f32_e32 v1, 0xbfb8aa3b, v1
	v_exp_f32_e32 v1, v1
	s_nop 0
	v_add_f32_e32 v1, 1.0, v1
	s_nop 0
	v_add_f32_e32 v3, 2.0, v0
	v_rcp_f32_e32 v1, v1
	s_nop 0
	v_add_f32_e32 v2, 1.0, v0
	v_mul_f32_e64 v0, v3, -v0
	v_cmp_gt_f32_e32 vcc, s28, v0
	v_mul_f32_e32 v3, 0x4f800000, v0
	s_nop 0
	v_cndmask_b32_e32 v0, v0, v3, vcc
	v_sqrt_f32_e32 v3, v0
	s_nop 0
	v_add_u32_e32 v4, -1, v3
	v_fma_f32 v5, -v4, v3, v0
	v_cmp_ge_f32_e64 s[0:1], 0, v5
	v_add_u32_e32 v5, 1, v3
	s_nop 0
	v_cndmask_b32_e64 v4, v3, v4, s[0:1]
	v_fma_f32 v3, -v5, v3, v0
	v_cmp_lt_f32_e64 s[0:1], 0, v3
	s_nop 1
	v_cndmask_b32_e64 v3, v4, v5, s[0:1]
	v_mul_f32_e32 v4, 0x37800000, v3
	v_cndmask_b32_e32 v3, v3, v4, vcc
	v_cmp_class_f32_e32 vcc, v0, v160
	s_nop 1
	v_cndmask_b32_e32 v0, v3, v0, vcc
	ds_read_b32 v3, v81 offset:15872
	s_waitcnt lgkmcnt(0)
	v_mul_f32_e32 v1, v1, v3
	v_mul_f32_e32 v0, v1, v0
	ds_write_b32 v81, v2 offset:50688
	ds_write_b32 v98, v0
	v_add_f32_e32 v0, v85, v31
	v_mul_f32_e32 v0, 0xbfb8aa3b, v0
	v_exp_f32_e32 v0, v0
	s_nop 0
	v_add_f32_e32 v0, 1.0, v0
	s_nop 0
	v_rcp_f32_e32 v0, v0
	s_nop 0
	v_mul_f32_e32 v0, 0xc1000000, v0
	v_mul_f32_e32 v1, v0, v32
	v_fmamk_f32 v0, v1, 0x3ab60b61, v158
	v_fmaak_f32 v0, v1, v0, 0x3d2aaaab
	v_fmaak_f32 v0, v1, v0, 0x3e2aaaab
	v_fma_f32 v0, v1, v0, 0.5
	v_fma_f32 v0, v1, v0, 1.0
	v_mul_f32_e32 v0, v1, v0
	v_cmp_gt_f32_e32 vcc, s95, v1
	s_and_saveexec_b64 s[0:1], vcc
	s_cbranch_execz .LBB0_328
	v_mul_f32_e32 v0, 0x3fb8aa3b, v1
	v_rndne_f32_e32 v0, v0
	v_fmamk_f32 v2, v0, 0xbf317218, v1
	v_fmac_f32_e32 v2, 0x3102e308, v0
	v_fmamk_f32 v3, v2, 0x395133b1, v159
	v_cmp_eq_f32_e32 vcc, s96, v0
	v_cvt_i32_f32_e32 v0, v0
	v_fmaak_f32 v3, v2, v3, 0x3c0887f9
	v_fmaak_f32 v3, v2, v3, 0x3d2aaa81
	v_fmaak_f32 v3, v2, v3, 0x3e2aaaab
	v_fma_f32 v3, v2, v3, 0.5
	v_ldexp_f32 v0, 1.0, v0
	v_mul_f32_e32 v3, v2, v3
	v_cndmask_b32_e32 v0, v0, v171, vcc
	v_fmac_f32_e32 v2, v2, v3
	v_add_f32_e32 v3, -1.0, v0
	v_fmac_f32_e32 v3, v0, v2
	v_add_f32_e32 v0, v3, v3
	v_cndmask_b32_e32 v0, v3, v0, vcc
	v_cmp_ngt_f32_e32 vcc, s97, v1
	s_nop 1
	v_cndmask_b32_e32 v0, -1.0, v0, vcc
.LBB0_328:
	s_or_b64 exec, exec, s[0:1]
	v_add_f32_e32 v1, v84, v15
	v_mul_f32_e32 v1, 0xbfb8aa3b, v1
	v_exp_f32_e32 v1, v1
	v_add_f32_e32 v2, 2.0, v0
	v_mul_f32_e64 v2, v2, -v0
	v_sub_u32_e32 v30, 63, v48
	v_add_f32_e32 v1, 1.0, v1
	v_add_f32_e32 v0, 1.0, v0
	v_mul_f32_e32 v4, 0x4f800000, v2
	v_cmp_gt_f32_e32 vcc, s28, v2
	v_rcp_f32_e32 v1, v1
	s_nop 0
	v_lshl_or_b32 v31, v30, 8, v83
	v_cndmask_b32_e32 v2, v2, v4, vcc
	v_sqrt_f32_e32 v4, v2
	v_sub_u32_e32 v28, 63, v50
	v_lshl_or_b32 v29, v28, 8, v83
	v_sub_u32_e32 v26, 63, v52
	v_add_u32_e32 v3, -1, v4
	v_fma_f32 v5, -v3, v4, v2
	v_cmp_ge_f32_e64 s[0:1], 0, v5
	v_add_u32_e32 v5, 1, v4
	v_lshl_or_b32 v27, v26, 8, v83
	v_cndmask_b32_e64 v3, v4, v3, s[0:1]
	v_fma_f32 v4, -v5, v4, v2
	v_cmp_lt_f32_e64 s[0:1], 0, v4
	ds_read_b32 v4, v81 offset:16128
	v_sub_u32_e32 v24, 63, v54
	v_cndmask_b32_e64 v3, v3, v5, s[0:1]
	v_mul_f32_e32 v5, 0x37800000, v3
	v_cndmask_b32_e32 v3, v3, v5, vcc
	v_cmp_class_f32_e32 vcc, v2, v160
	s_waitcnt lgkmcnt(0)
	v_mul_f32_e32 v1, v1, v4
	v_lshl_or_b32 v25, v24, 8, v83
	v_cndmask_b32_e32 v2, v3, v2, vcc
	v_mul_f32_e32 v1, v1, v2
	ds_write_b32 v81, v0 offset:50944
	ds_write_b32 v96, v1
	s_waitcnt lgkmcnt(0)
	s_barrier
	ds_read2st64_b32 v[0:1], v31 offset0:172 offset1:236
	v_sub_u32_e32 v22, 63, v56
	v_lshl_or_b32 v23, v22, 8, v83
	v_sub_u32_e32 v20, 63, v58
	v_lshl_or_b32 v21, v20, 8, v83
	s_waitcnt lgkmcnt(0)
	v_fma_f32 v1, 0, v0, v1
	ds_write_b32 v31, v1 offset:60416
	ds_read2st64_b32 v[2:3], v29 offset0:172 offset1:236
	v_sub_u32_e32 v18, 63, v60
	v_lshl_or_b32 v19, v18, 8, v83
	v_sub_u32_e32 v16, 63, v62
	v_lshl_or_b32 v17, v16, 8, v83
	s_waitcnt lgkmcnt(0)
	v_mul_f32_e32 v4, v0, v2
	v_fmac_f32_e32 v3, v1, v2
	ds_write2st64_b32 v29, v4, v3 offset0:172 offset1:236
	ds_read2st64_b32 v[0:1], v27 offset0:172 offset1:236
	v_sub_u32_e32 v14, 63, v64
	v_lshl_or_b32 v15, v14, 8, v83
	v_sub_u32_e32 v12, 63, v66
	v_lshl_or_b32 v13, v12, 8, v83
	s_waitcnt lgkmcnt(0)
	v_mul_f32_e32 v4, v4, v0
	v_fmac_f32_e32 v1, v3, v0
	ds_write2st64_b32 v27, v4, v1 offset0:172 offset1:236
	ds_read2st64_b32 v[2:3], v25 offset0:172 offset1:236
	v_sub_u32_e32 v10, 63, v68
	v_lshl_or_b32 v11, v10, 8, v83
	v_sub_u32_e32 v8, 63, v70
	v_lshl_or_b32 v9, v8, 8, v83
	s_waitcnt lgkmcnt(0)
	v_mul_f32_e32 v4, v4, v2
	v_fmac_f32_e32 v3, v1, v2
	ds_write2st64_b32 v25, v4, v3 offset0:172 offset1:236
	ds_read2st64_b32 v[0:1], v23 offset0:172 offset1:236
	v_sub_u32_e32 v6, 63, v72
	v_lshl_or_b32 v7, v6, 8, v83
	s_waitcnt lgkmcnt(0)
	v_mul_f32_e32 v4, v4, v0
	v_fmac_f32_e32 v1, v3, v0
	ds_write2st64_b32 v23, v4, v1 offset0:172 offset1:236
	ds_read2st64_b32 v[2:3], v21 offset0:172 offset1:236
	s_waitcnt lgkmcnt(0)
	v_mul_f32_e32 v4, v4, v2
	v_fmac_f32_e32 v3, v1, v2
	ds_write2st64_b32 v21, v4, v3 offset0:172 offset1:236
	ds_read2st64_b32 v[0:1], v19 offset0:172 offset1:236
	s_waitcnt lgkmcnt(0)
	v_mul_f32_e32 v4, v4, v0
	v_fmac_f32_e32 v1, v3, v0
	ds_write2st64_b32 v19, v4, v1 offset0:172 offset1:236
	ds_read2st64_b32 v[2:3], v17 offset0:172 offset1:236
	s_waitcnt lgkmcnt(0)
	v_mul_f32_e32 v4, v4, v2
	v_fmac_f32_e32 v3, v1, v2
	ds_write2st64_b32 v17, v4, v3 offset0:172 offset1:236
	ds_read2st64_b32 v[0:1], v15 offset0:172 offset1:236
	s_waitcnt lgkmcnt(0)
	v_mul_f32_e32 v4, v4, v0
	v_fmac_f32_e32 v1, v3, v0
	ds_write2st64_b32 v15, v4, v1 offset0:172 offset1:236
	ds_read2st64_b32 v[2:3], v13 offset0:172 offset1:236
	s_waitcnt lgkmcnt(0)
	v_mul_f32_e32 v4, v4, v2
	v_fmac_f32_e32 v3, v1, v2
	ds_write2st64_b32 v13, v4, v3 offset0:172 offset1:236
	ds_read2st64_b32 v[0:1], v11 offset0:172 offset1:236
	s_waitcnt lgkmcnt(0)
	v_mul_f32_e32 v4, v4, v0
	v_fmac_f32_e32 v1, v3, v0
	ds_write2st64_b32 v11, v4, v1 offset0:172 offset1:236
	ds_read2st64_b32 v[2:3], v9 offset0:172 offset1:236
	s_waitcnt lgkmcnt(0)
	v_mul_f32_e32 v5, v4, v2
	v_fmac_f32_e32 v3, v1, v2
	ds_write2st64_b32 v9, v5, v3 offset0:172 offset1:236
	ds_read2st64_b32 v[0:1], v7 offset0:172 offset1:236
	v_sub_u32_e32 v4, 63, v74
	v_sub_u32_e32 v2, 63, v76
	s_waitcnt lgkmcnt(0)
	v_mul_f32_e32 v34, v5, v0
	v_fmac_f32_e32 v1, v3, v0
	ds_write2st64_b32 v7, v34, v1 offset0:172 offset1:236
	v_lshl_or_b32 v5, v4, 8, v83
	ds_read2st64_b32 v[32:33], v5 offset0:172 offset1:236
	v_lshl_or_b32 v3, v2, 8, v83
	v_sub_u32_e32 v0, 63, v78
	s_waitcnt lgkmcnt(0)
	v_mul_f32_e32 v36, v34, v32
	v_fmac_f32_e32 v33, v1, v32
	ds_write2st64_b32 v5, v36, v33 offset0:172 offset1:236
	ds_read2st64_b32 v[34:35], v3 offset0:172 offset1:236
	v_mov_b32_e32 v32, 1.0
	v_mov_b32_e32 v1, 0
	s_waitcnt lgkmcnt(0)
	v_mul_f32_e32 v38, v36, v34
	v_fmac_f32_e32 v35, v33, v34
	ds_write2st64_b32 v3, v38, v35 offset0:172 offset1:236
	v_lshl_or_b32 v33, v0, 8, v83
	ds_read2st64_b32 v[36:37], v33 offset0:172 offset1:236
	s_waitcnt lgkmcnt(0)
	v_mul_f32_e32 v34, v38, v36
	v_fmac_f32_e32 v37, v35, v36
	ds_write2st64_b32 v33, v34, v37 offset0:172 offset1:236
	ds_write_b32 v86, v34
	ds_write_b32 v92, v37
	s_waitcnt lgkmcnt(0)
	s_barrier
	s_and_saveexec_b64 s[0:1], s[42:43]
	s_cbranch_execz .LBB0_334
	ds_read_b32 v32, v89
	ds_read_b32 v1, v88
	s_waitcnt lgkmcnt(0)
	v_fmac_f32_e32 v1, 0, v32
	s_or_b64 exec, exec, s[0:1]
	s_and_saveexec_b64 s[0:1], s[44:45]
	s_cbranch_execnz .LBB0_335
